# exact counted waits for the hoisted epilogue base loads in the ffn1-down, w_out and w_o_mem GEMMs
# speedup vs baseline: 1.0024x; 1.0024x over previous
; __device__ __forceinline__ unsigned cvt_pk_bf16(float lo, float hi) { unsigned r; asm volatile("v_cvt_pk_bf16_f32 %0, %1, %2" : "=v"(r) : "v"(lo), "v"(hi)); return r; }
;     __device__ __forceinline__ void operator()(const f32x4 (&acc)[2][2][4][2], const Unit& u, int wr, int wc, int fr, int fq) const {
;     ...
;             for (int m = 0; m < 4; ++m) { const int row = row0 + ai * HALF + m * 16; const size_t off = (size_t)row * ldc + col0; float part = 0.f;
; #pragma unroll
;                 for (int bj = 0; bj < 2; ++bj) { const size_t idx = off + bj * HALF;
;                     f32x4 b0, b1;
;                     if constexpr (BASE_BF16) { const u32x4 r = *(const u32x4*)(baseb + idx);
;                         b0 = (f32x4){__builtin_bit_cast(float, r.x << 16), __builtin_bit_cast(float, r.x & 0xffff0000u), __builtin_bit_cast(float, r.y << 16), __builtin_bit_cast(float, r.y & 0xffff0000u)};
;                         b1 = (f32x4){__builtin_bit_cast(float, r.z << 16), __builtin_bit_cast(float, r.z & 0xffff0000u), __builtin_bit_cast(float, r.w << 16), __builtin_bit_cast(float, r.w & 0xffff0000u)}; }
;                     else { b0 = *(const f32x4*)(base + idx); b1 = *(const f32x4*)(base + idx + 4); }
;                     const f32x4 o0 = b0 + acc[ai][bj][m][0] * alpha, o1 = b1 + acc[ai][bj][m][1] * alpha;
;                     if constexpr (WRITE_F32) { *(f32x4*)(out + idx) = o0; *(f32x4*)(out + idx + 4) = o1; }
;                     if constexpr (WRITE_XB) {
;                         part += (o0[0] * o0[0] + o0[1] * o0[1]) + (o0[2] * o0[2] + o0[3] * o0[3]) + (o1[0] * o1[0] + o1[1] * o1[1]) + (o1[2] * o1[2] + o1[3] * o1[3]);
;                         u32x4 w; w.x = cvt_pk_bf16(o0[0], o0[1]); w.y = cvt_pk_bf16(o0[2], o0[3]); w.z = cvt_pk_bf16(o1[0], o1[1]); w.w = cvt_pk_bf16(o1[2], o1[3]);
;                         *(u32x4*)(xb + idx) = w; } }
;                 if constexpr (WRITE_XB) { part += __shfl_xor(part, 16); part += __shfl_xor(part, 32);
;                     if (fq == 0) atomicAdd(ss + row, part); } }
.LBB0_262:
	v_lshl_add_u32 v146, s28, 8, v148
	v_lshl_or_b32 v144, s29, 8, v150
	v_ashrrev_i32_e32 v147, 31, v146
	v_ashrrev_i32_e32 v145, 31, v144
	v_mov_b32_e32 v248, v146
	v_lshl_add_u32 v248, v248, 11, v144
	v_lshlrev_b32_e32 v248, 2, v248
	global_load_dwordx4 v[172:175], v248, s[52:53]
	global_load_dwordx4 v[176:179], v248, s[52:53] offset:16
	global_load_dwordx4 v[180:183], v248, s[52:53] offset:512
	global_load_dwordx4 v[184:187], v248, s[52:53] offset:528
	v_add_u32_e32 v249, 16, v146
	v_lshl_add_u32 v249, v249, 11, v144
	v_lshlrev_b32_e32 v249, 2, v249
	global_load_dwordx4 v[188:191], v249, s[52:53]
	global_load_dwordx4 v[192:195], v249, s[52:53] offset:16
	global_load_dwordx4 v[196:199], v249, s[52:53] offset:512
	global_load_dwordx4 v[200:203], v249, s[52:53] offset:528
	v_add_u32_e32 v250, 32, v146
	v_lshl_add_u32 v250, v250, 11, v144
	v_lshlrev_b32_e32 v250, 2, v250
	global_load_dwordx4 v[204:207], v250, s[52:53]
	global_load_dwordx4 v[208:211], v250, s[52:53] offset:16
	global_load_dwordx4 v[212:215], v250, s[52:53] offset:512
	global_load_dwordx4 v[220:223], v250, s[52:53] offset:528
	v_add_u32_e32 v251, 48, v146
	v_lshl_add_u32 v251, v251, 11, v144
	v_lshlrev_b32_e32 v251, 2, v251
	global_load_dwordx4 v[224:227], v251, s[52:53]
	global_load_dwordx4 v[228:231], v251, s[52:53] offset:16
	global_load_dwordx4 v[232:235], v251, s[52:53] offset:512
	global_load_dwordx4 v[236:239], v251, s[52:53] offset:528
	v_lshlrev_b64 v[156:157], 11, v[146:147]
	v_lshl_add_u64 v[164:165], v[156:157], 0, v[144:145]
	v_lshl_add_u64 v[166:167], v[164:165], 2, s[52:53]
	s_waitcnt vmcnt(15)
	s_nop 1
	v_mov_b32_e32 v156, v172
	v_mov_b32_e32 v157, v173
	v_mov_b32_e32 v158, v174
	v_mov_b32_e32 v159, v175
	s_waitcnt vmcnt(14)
	s_nop 1
	v_mov_b32_e32 v160, v176
	v_mov_b32_e32 v161, v177
	v_mov_b32_e32 v162, v178
	v_mov_b32_e32 v163, v179
	v_lshlrev_b64 v[164:165], 1, v[164:165]
	v_lshl_add_u64 v[168:169], s[16:17], 0, v[164:165]
	v_xor_b32_e32 v155, 32, v154
	v_or_b32_e32 v164, 0x100, v164
	v_pk_fma_f32 v[126:127], v[126:127], 0.5, v[158:159] op_sel_hi:[1,0,1]
	v_pk_fma_f32 v[170:171], v[124:125], 0.5, v[156:157] op_sel_hi:[1,0,1]
	v_pk_fma_f32 v[162:163], v[122:123], 0.5, v[162:163] op_sel_hi:[1,0,1]
	v_pk_fma_f32 v[160:161], v[120:121], 0.5, v[160:161] op_sel_hi:[1,0,1]
	v_cvt_pk_bf16_f32 v120, v170, v171
	v_cvt_pk_bf16_f32 v121, v126, v127
	v_mul_f32_e32 v127, v127, v127
	v_cvt_pk_bf16_f32 v122, v160, v161
	v_cvt_pk_bf16_f32 v123, v162, v163
	global_store_dwordx4 v[168:169], v[120:123], off
	s_waitcnt vmcnt(14)
	s_nop 1
	v_mov_b32_e32 v122, v180
	v_mov_b32_e32 v123, v181
	v_mov_b32_e32 v124, v182
	v_mov_b32_e32 v125, v183
	s_nop 0
	s_waitcnt vmcnt(13)
	s_nop 1
	v_mov_b32_e32 v156, v184
	v_mov_b32_e32 v157, v185
	v_mov_b32_e32 v158, v186
	v_mov_b32_e32 v159, v187
	v_mul_f32_e32 v166, v171, v171
	v_and_b32_e32 v121, 64, v154
	v_mul_f32_e32 v161, v161, v161
	v_fmac_f32_e32 v166, v170, v170
	v_fmac_f32_e32 v127, v126, v126
	v_xor_b32_e32 v120, 16, v154
	v_add_u32_e32 v121, 64, v121
	v_mul_f32_e32 v163, v163, v163
	v_fmac_f32_e32 v161, v160, v160
	v_add_f32_e32 v126, v166, v127
	v_cmp_lt_i32_e32 vcc, v120, v121
	v_fmac_f32_e32 v163, v162, v162
	v_add_f32_e32 v126, v161, v126
	v_cndmask_b32_e32 v120, v154, v120, vcc
	v_add_f32_e32 v126, v163, v126
	v_lshlrev_b32_e32 v120, 2, v120
	v_cmp_lt_i32_e32 vcc, v155, v121
	v_pk_fma_f32 v[118:119], v[118:119], 0.5, v[124:125] op_sel_hi:[1,0,1]
	v_pk_fma_f32 v[116:117], v[116:117], 0.5, v[122:123] op_sel_hi:[1,0,1]
	v_pk_fma_f32 v[122:123], v[114:115], 0.5, v[158:159] op_sel_hi:[1,0,1]
	v_pk_fma_f32 v[112:113], v[112:113], 0.5, v[156:157] op_sel_hi:[1,0,1]
	v_mul_f32_e32 v114, v117, v117
	v_mul_f32_e32 v115, v119, v119
	v_mul_f32_e32 v124, v113, v113
	v_fmac_f32_e32 v114, v116, v116
	v_fmac_f32_e32 v115, v118, v118
	v_mul_f32_e32 v125, v123, v123
	v_fmac_f32_e32 v124, v112, v112
	v_add_f32_e32 v114, v114, v115
	v_fmac_f32_e32 v125, v122, v122
	v_add_f32_e32 v114, v124, v114
	v_add_f32_e32 v114, v125, v114
	v_add_f32_e32 v114, v126, v114
	ds_bpermute_b32 v115, v120, v114
	v_cndmask_b32_e32 v121, v154, v155, vcc
	v_cvt_pk_bf16_f32 v116, v116, v117
	v_cvt_pk_bf16_f32 v117, v118, v119
	v_cvt_pk_bf16_f32 v118, v112, v113
	s_waitcnt lgkmcnt(0)
	v_add_f32_e32 v112, v114, v115
	v_lshlrev_b32_e32 v114, 2, v121
	ds_bpermute_b32 v113, v114, v112
	v_cvt_pk_bf16_f32 v119, v122, v123
	v_lshl_add_u64 v[122:123], s[16:17], 0, v[164:165]
	global_store_dwordx4 v[122:123], v[116:119], off
	s_and_saveexec_b64 s[46:47], s[2:3]
	s_cbranch_execz .LBB0_264
	v_lshl_add_u64 v[116:117], v[146:147], 2, s[18:19]
	s_waitcnt lgkmcnt(0)
	v_add_f32_e32 v112, v112, v113
	global_atomic_add_f32 v[116:117], v112, off
; __device__ __forceinline__ unsigned cvt_pk_bf16(float lo, float hi) { unsigned r; asm volatile("v_cvt_pk_bf16_f32 %0, %1, %2" : "=v"(r) : "v"(lo), "v"(hi)); return r; }
;     __device__ __forceinline__ void operator()(const f32x4 (&acc)[2][2][4][2], const Unit& u, int wr, int wc, int fr, int fq) const {
;     ...
;             for (int m = 0; m < 4; ++m) { const int row = row0 + ai * HALF + m * 16; const size_t off = (size_t)row * ldc + col0; float part = 0.f;
; #pragma unroll
;                 for (int bj = 0; bj < 2; ++bj) { const size_t idx = off + bj * HALF;
;                     f32x4 b0, b1;
;                     if constexpr (BASE_BF16) { const u32x4 r = *(const u32x4*)(baseb + idx);
;                         b0 = (f32x4){__builtin_bit_cast(float, r.x << 16), __builtin_bit_cast(float, r.x & 0xffff0000u), __builtin_bit_cast(float, r.y << 16), __builtin_bit_cast(float, r.y & 0xffff0000u)};
;                         b1 = (f32x4){__builtin_bit_cast(float, r.z << 16), __builtin_bit_cast(float, r.z & 0xffff0000u), __builtin_bit_cast(float, r.w << 16), __builtin_bit_cast(float, r.w & 0xffff0000u)}; }
;                     else { b0 = *(const f32x4*)(base + idx); b1 = *(const f32x4*)(base + idx + 4); }
;                     const f32x4 o0 = b0 + acc[ai][bj][m][0] * alpha, o1 = b1 + acc[ai][bj][m][1] * alpha;
;                     if constexpr (WRITE_F32) { *(f32x4*)(out + idx) = o0; *(f32x4*)(out + idx + 4) = o1; }
;                     if constexpr (WRITE_XB) {
;                         part += (o0[0] * o0[0] + o0[1] * o0[1]) + (o0[2] * o0[2] + o0[3] * o0[3]) + (o1[0] * o1[0] + o1[1] * o1[1]) + (o1[2] * o1[2] + o1[3] * o1[3]);
;                         u32x4 w; w.x = cvt_pk_bf16(o0[0], o0[1]); w.y = cvt_pk_bf16(o0[2], o0[3]); w.z = cvt_pk_bf16(o1[0], o1[1]); w.w = cvt_pk_bf16(o1[2], o1[3]);
;                         *(u32x4*)(xb + idx) = w; } }
;                 if constexpr (WRITE_XB) { part += __shfl_xor(part, 16); part += __shfl_xor(part, 32);
;                     if (fq == 0) atomicAdd(ss + row, part); } }
.LBB0_264:
	s_or_b64 exec, exec, s[46:47]
	v_or_b32_e32 v112, 16, v146
	s_waitcnt lgkmcnt(0)
	v_ashrrev_i32_e32 v113, 31, v112
	v_lshlrev_b64 v[116:117], 11, v[112:113]
	v_lshl_add_u64 v[126:127], v[116:117], 0, v[144:145]
	v_lshl_add_u64 v[156:157], v[126:127], 2, s[52:53]
	s_waitcnt vmcnt(14)
	s_nop 1
	v_mov_b32_e32 v116, v188
	v_mov_b32_e32 v117, v189
	v_mov_b32_e32 v118, v190
	v_mov_b32_e32 v119, v191
	s_waitcnt vmcnt(13)
	s_nop 1
	v_mov_b32_e32 v122, v192
	v_mov_b32_e32 v123, v193
	v_mov_b32_e32 v124, v194
	v_mov_b32_e32 v125, v195
	v_lshlrev_b64 v[126:127], 1, v[126:127]
	v_lshl_add_u64 v[158:159], s[16:17], 0, v[126:127]
	v_or_b32_e32 v126, 0x100, v126
	v_pk_fma_f32 v[118:119], v[110:111], 0.5, v[118:119] op_sel_hi:[1,0,1]
	v_pk_fma_f32 v[116:117], v[108:109], 0.5, v[116:117] op_sel_hi:[1,0,1]
	v_pk_fma_f32 v[124:125], v[106:107], 0.5, v[124:125] op_sel_hi:[1,0,1]
	v_pk_fma_f32 v[122:123], v[104:105], 0.5, v[122:123] op_sel_hi:[1,0,1]
	v_cvt_pk_bf16_f32 v104, v116, v117
	v_cvt_pk_bf16_f32 v105, v118, v119
	v_mul_f32_e32 v115, v117, v117
	v_cvt_pk_bf16_f32 v106, v122, v123
	v_cvt_pk_bf16_f32 v107, v124, v125
	global_store_dwordx4 v[158:159], v[104:107], off
	s_waitcnt vmcnt(13)
	s_nop 1
	v_mov_b32_e32 v104, v196
	v_mov_b32_e32 v105, v197
	v_mov_b32_e32 v106, v198
	v_mov_b32_e32 v107, v199
	s_nop 0
	s_waitcnt vmcnt(12)
	s_nop 1
	v_mov_b32_e32 v108, v200
	v_mov_b32_e32 v109, v201
	v_mov_b32_e32 v110, v202
	v_mov_b32_e32 v111, v203
	v_mul_f32_e32 v117, v119, v119
	v_mul_f32_e32 v119, v123, v123
	v_fmac_f32_e32 v115, v116, v116
	v_fmac_f32_e32 v117, v118, v118
	v_mul_f32_e32 v121, v125, v125
	v_fmac_f32_e32 v119, v122, v122
	v_add_f32_e32 v115, v115, v117
	v_fmac_f32_e32 v121, v124, v124
	v_add_f32_e32 v115, v119, v115
	v_add_f32_e32 v115, v121, v115
	v_pk_fma_f32 v[102:103], v[102:103], 0.5, v[106:107] op_sel_hi:[1,0,1]
	v_pk_fma_f32 v[100:101], v[100:101], 0.5, v[104:105] op_sel_hi:[1,0,1]
	v_pk_fma_f32 v[104:105], v[98:99], 0.5, v[110:111] op_sel_hi:[1,0,1]
	v_pk_fma_f32 v[96:97], v[96:97], 0.5, v[108:109] op_sel_hi:[1,0,1]
	v_mul_f32_e32 v98, v101, v101
	v_mul_f32_e32 v99, v103, v103
	v_mul_f32_e32 v106, v97, v97
	v_fmac_f32_e32 v98, v100, v100
	v_fmac_f32_e32 v99, v102, v102
	v_mul_f32_e32 v107, v105, v105
	v_fmac_f32_e32 v106, v96, v96
	v_add_f32_e32 v98, v98, v99
	v_add_f32_e32 v98, v106, v98
	v_fmac_f32_e32 v107, v104, v104
	v_add_f32_e32 v98, v107, v98
	v_add_f32_e32 v106, v115, v98
	ds_bpermute_b32 v107, v120, v106
	v_cvt_pk_bf16_f32 v98, v100, v101
	v_cvt_pk_bf16_f32 v99, v102, v103
	v_cvt_pk_bf16_f32 v100, v96, v97
	v_lshl_add_u64 v[102:103], s[16:17], 0, v[126:127]
	s_waitcnt lgkmcnt(0)
	v_add_f32_e32 v96, v106, v107
	ds_bpermute_b32 v97, v114, v96
	v_cvt_pk_bf16_f32 v101, v104, v105
	global_store_dwordx4 v[102:103], v[98:101], off
	s_and_saveexec_b64 s[46:47], s[2:3]
	s_cbranch_execz .LBB0_266
	v_lshl_add_u64 v[98:99], v[112:113], 2, s[18:19]
	s_waitcnt lgkmcnt(0)
	v_add_f32_e32 v96, v96, v97
	global_atomic_add_f32 v[98:99], v96, off
.LBB0_266:
	s_or_b64 exec, exec, s[46:47]
	v_or_b32_e32 v96, 32, v146
	s_waitcnt lgkmcnt(0)
	v_ashrrev_i32_e32 v97, 31, v96
	v_lshlrev_b64 v[98:99], 11, v[96:97]
	v_lshl_add_u64 v[106:107], v[98:99], 0, v[144:145]
	v_lshl_add_u64 v[108:109], v[106:107], 2, s[52:53]
	s_waitcnt vmcnt(13)
	s_nop 1
	v_mov_b32_e32 v98, v204
	v_mov_b32_e32 v99, v205
	v_mov_b32_e32 v100, v206
	v_mov_b32_e32 v101, v207
	s_waitcnt vmcnt(12)
	s_nop 1
	v_mov_b32_e32 v102, v208
	v_mov_b32_e32 v103, v209
	v_mov_b32_e32 v104, v210
	v_mov_b32_e32 v105, v211
	v_lshlrev_b64 v[106:107], 1, v[106:107]
	v_lshl_add_u64 v[110:111], s[16:17], 0, v[106:107]
	v_or_b32_e32 v106, 0x100, v106
	v_pk_fma_f32 v[100:101], v[94:95], 0.5, v[100:101] op_sel_hi:[1,0,1]
	v_pk_fma_f32 v[98:99], v[92:93], 0.5, v[98:99] op_sel_hi:[1,0,1]
	v_pk_fma_f32 v[104:105], v[90:91], 0.5, v[104:105] op_sel_hi:[1,0,1]
	v_pk_fma_f32 v[102:103], v[88:89], 0.5, v[102:103] op_sel_hi:[1,0,1]
	v_cvt_pk_bf16_f32 v88, v98, v99
	v_cvt_pk_bf16_f32 v89, v100, v101
	v_mul_f32_e32 v99, v99, v99
	v_cvt_pk_bf16_f32 v90, v102, v103
	v_cvt_pk_bf16_f32 v91, v104, v105
	global_store_dwordx4 v[110:111], v[88:91], off
	s_waitcnt vmcnt(12)
	s_nop 1
	v_mov_b32_e32 v88, v212
	v_mov_b32_e32 v89, v213
	v_mov_b32_e32 v90, v214
	v_mov_b32_e32 v91, v215
	s_nop 0
	s_waitcnt vmcnt(11)
	s_nop 1
	v_mov_b32_e32 v92, v220
	v_mov_b32_e32 v93, v221
	v_mov_b32_e32 v94, v222
	v_mov_b32_e32 v95, v223
	v_mul_f32_e32 v101, v101, v101
	v_mul_f32_e32 v103, v103, v103
	v_fmac_f32_e32 v99, v98, v98
	v_fmac_f32_e32 v101, v100, v100
	v_mul_f32_e32 v105, v105, v105
	v_fmac_f32_e32 v103, v102, v102
	v_add_f32_e32 v98, v99, v101
	v_fmac_f32_e32 v105, v104, v104
	v_add_f32_e32 v98, v103, v98
	v_add_f32_e32 v98, v105, v98
	v_pk_fma_f32 v[86:87], v[86:87], 0.5, v[90:91] op_sel_hi:[1,0,1]
	v_pk_fma_f32 v[84:85], v[84:85], 0.5, v[88:89] op_sel_hi:[1,0,1]
	v_pk_fma_f32 v[88:89], v[82:83], 0.5, v[94:95] op_sel_hi:[1,0,1]
	v_pk_fma_f32 v[80:81], v[80:81], 0.5, v[92:93] op_sel_hi:[1,0,1]
	v_mul_f32_e32 v82, v85, v85
	v_mul_f32_e32 v83, v87, v87
	v_mul_f32_e32 v90, v81, v81
	v_fmac_f32_e32 v82, v84, v84
	v_fmac_f32_e32 v83, v86, v86
	v_mul_f32_e32 v91, v89, v89
	v_fmac_f32_e32 v90, v80, v80
	v_add_f32_e32 v82, v82, v83
	v_add_f32_e32 v82, v90, v82
	v_fmac_f32_e32 v91, v88, v88
	v_add_f32_e32 v82, v91, v82
	v_add_f32_e32 v90, v98, v82
	ds_bpermute_b32 v91, v120, v90
	v_cvt_pk_bf16_f32 v82, v84, v85
	v_cvt_pk_bf16_f32 v83, v86, v87
	v_cvt_pk_bf16_f32 v84, v80, v81
	v_lshl_add_u64 v[86:87], s[16:17], 0, v[106:107]
	s_waitcnt lgkmcnt(0)
	v_add_f32_e32 v80, v90, v91
	ds_bpermute_b32 v81, v114, v80
	v_cvt_pk_bf16_f32 v85, v88, v89
	global_store_dwordx4 v[86:87], v[82:85], off
	s_and_saveexec_b64 s[46:47], s[2:3]
	s_cbranch_execz .LBB0_268
	v_lshl_add_u64 v[82:83], v[96:97], 2, s[18:19]
	s_waitcnt lgkmcnt(0)
	v_add_f32_e32 v80, v80, v81
	global_atomic_add_f32 v[82:83], v80, off
; __device__ __forceinline__ unsigned cvt_pk_bf16(float lo, float hi) { unsigned r; asm volatile("v_cvt_pk_bf16_f32 %0, %1, %2" : "=v"(r) : "v"(lo), "v"(hi)); return r; }
;     __device__ __forceinline__ void operator()(const f32x4 (&acc)[2][2][4][2], const Unit& u, int wr, int wc, int fr, int fq) const {
;     ...
;             for (int m = 0; m < 4; ++m) { const int row = row0 + ai * HALF + m * 16; const size_t off = (size_t)row * ldc + col0; float part = 0.f;
; #pragma unroll
;                 for (int bj = 0; bj < 2; ++bj) { const size_t idx = off + bj * HALF;
;                     f32x4 b0, b1;
;                     if constexpr (BASE_BF16) { const u32x4 r = *(const u32x4*)(baseb + idx);
;                         b0 = (f32x4){__builtin_bit_cast(float, r.x << 16), __builtin_bit_cast(float, r.x & 0xffff0000u), __builtin_bit_cast(float, r.y << 16), __builtin_bit_cast(float, r.y & 0xffff0000u)};
;                         b1 = (f32x4){__builtin_bit_cast(float, r.z << 16), __builtin_bit_cast(float, r.z & 0xffff0000u), __builtin_bit_cast(float, r.w << 16), __builtin_bit_cast(float, r.w & 0xffff0000u)}; }
;                     else { b0 = *(const f32x4*)(base + idx); b1 = *(const f32x4*)(base + idx + 4); }
;                     const f32x4 o0 = b0 + acc[ai][bj][m][0] * alpha, o1 = b1 + acc[ai][bj][m][1] * alpha;
;                     if constexpr (WRITE_F32) { *(f32x4*)(out + idx) = o0; *(f32x4*)(out + idx + 4) = o1; }
;                     if constexpr (WRITE_XB) {
;                         part += (o0[0] * o0[0] + o0[1] * o0[1]) + (o0[2] * o0[2] + o0[3] * o0[3]) + (o1[0] * o1[0] + o1[1] * o1[1]) + (o1[2] * o1[2] + o1[3] * o1[3]);
;                         u32x4 w; w.x = cvt_pk_bf16(o0[0], o0[1]); w.y = cvt_pk_bf16(o0[2], o0[3]); w.z = cvt_pk_bf16(o1[0], o1[1]); w.w = cvt_pk_bf16(o1[2], o1[3]);
;                         *(u32x4*)(xb + idx) = w; } }
;                 if constexpr (WRITE_XB) { part += __shfl_xor(part, 16); part += __shfl_xor(part, 32);
;                     if (fq == 0) atomicAdd(ss + row, part); } }
.LBB0_268:
	s_or_b64 exec, exec, s[46:47]
	v_or_b32_e32 v80, 48, v146
	s_waitcnt lgkmcnt(0)
	v_ashrrev_i32_e32 v81, 31, v80
	v_lshlrev_b64 v[82:83], 11, v[80:81]
	v_lshl_add_u64 v[90:91], v[82:83], 0, v[144:145]
	v_lshl_add_u64 v[92:93], v[90:91], 2, s[52:53]
	s_waitcnt vmcnt(12)
	s_nop 1
	v_mov_b32_e32 v82, v224
	v_mov_b32_e32 v83, v225
	v_mov_b32_e32 v84, v226
	v_mov_b32_e32 v85, v227
	s_waitcnt vmcnt(11)
	s_nop 1
	v_mov_b32_e32 v86, v228
	v_mov_b32_e32 v87, v229
	v_mov_b32_e32 v88, v230
	v_mov_b32_e32 v89, v231
	v_lshlrev_b64 v[90:91], 1, v[90:91]
	v_lshl_add_u64 v[94:95], s[16:17], 0, v[90:91]
	v_or_b32_e32 v90, 0x100, v90
	v_pk_fma_f32 v[84:85], v[78:79], 0.5, v[84:85] op_sel_hi:[1,0,1]
	v_pk_fma_f32 v[82:83], v[76:77], 0.5, v[82:83] op_sel_hi:[1,0,1]
	v_pk_fma_f32 v[88:89], v[74:75], 0.5, v[88:89] op_sel_hi:[1,0,1]
	v_pk_fma_f32 v[86:87], v[72:73], 0.5, v[86:87] op_sel_hi:[1,0,1]
	v_cvt_pk_bf16_f32 v72, v82, v83
	v_cvt_pk_bf16_f32 v73, v84, v85
	v_mul_f32_e32 v83, v83, v83
	v_cvt_pk_bf16_f32 v74, v86, v87
	v_cvt_pk_bf16_f32 v75, v88, v89
	global_store_dwordx4 v[94:95], v[72:75], off
	s_waitcnt vmcnt(11)
	s_nop 1
	v_mov_b32_e32 v72, v232
	v_mov_b32_e32 v73, v233
	v_mov_b32_e32 v74, v234
	v_mov_b32_e32 v75, v235
	s_nop 0
	s_waitcnt vmcnt(10)
	s_nop 1
	v_mov_b32_e32 v76, v236
	v_mov_b32_e32 v77, v237
	v_mov_b32_e32 v78, v238
	v_mov_b32_e32 v79, v239
	v_add_u32_e32 v248, 0x80, v146
	v_lshl_add_u32 v248, v248, 11, v144
	v_lshlrev_b32_e32 v248, 2, v248
	global_load_dwordx4 v[172:175], v248, s[52:53]
	global_load_dwordx4 v[176:179], v248, s[52:53] offset:16
	global_load_dwordx4 v[180:183], v248, s[52:53] offset:512
	global_load_dwordx4 v[184:187], v248, s[52:53] offset:528
	v_add_u32_e32 v249, 0x90, v146
	v_lshl_add_u32 v249, v249, 11, v144
	v_lshlrev_b32_e32 v249, 2, v249
	global_load_dwordx4 v[188:191], v249, s[52:53]
	global_load_dwordx4 v[192:195], v249, s[52:53] offset:16
	global_load_dwordx4 v[196:199], v249, s[52:53] offset:512
	global_load_dwordx4 v[200:203], v249, s[52:53] offset:528
	v_add_u32_e32 v250, 0xa0, v146
	v_lshl_add_u32 v250, v250, 11, v144
	v_lshlrev_b32_e32 v250, 2, v250
	global_load_dwordx4 v[204:207], v250, s[52:53]
	global_load_dwordx4 v[208:211], v250, s[52:53] offset:16
	global_load_dwordx4 v[212:215], v250, s[52:53] offset:512
	global_load_dwordx4 v[220:223], v250, s[52:53] offset:528
	v_add_u32_e32 v251, 0xb0, v146
	v_lshl_add_u32 v251, v251, 11, v144
	v_lshlrev_b32_e32 v251, 2, v251
	global_load_dwordx4 v[224:227], v251, s[52:53]
	global_load_dwordx4 v[228:231], v251, s[52:53] offset:16
	global_load_dwordx4 v[232:235], v251, s[52:53] offset:512
	global_load_dwordx4 v[236:239], v251, s[52:53] offset:528
	v_mul_f32_e32 v85, v85, v85
	v_mul_f32_e32 v87, v87, v87
	v_fmac_f32_e32 v83, v82, v82
	v_fmac_f32_e32 v85, v84, v84
	v_mul_f32_e32 v89, v89, v89
	v_fmac_f32_e32 v87, v86, v86
	v_add_f32_e32 v82, v83, v85
	v_fmac_f32_e32 v89, v88, v88
	v_add_f32_e32 v82, v87, v82
	v_add_f32_e32 v82, v89, v82
	v_pk_fma_f32 v[70:71], v[70:71], 0.5, v[74:75] op_sel_hi:[1,0,1]
	v_pk_fma_f32 v[68:69], v[68:69], 0.5, v[72:73] op_sel_hi:[1,0,1]
	v_pk_fma_f32 v[72:73], v[66:67], 0.5, v[78:79] op_sel_hi:[1,0,1]
	v_pk_fma_f32 v[64:65], v[64:65], 0.5, v[76:77] op_sel_hi:[1,0,1]
	v_mul_f32_e32 v66, v69, v69
	v_mul_f32_e32 v67, v71, v71
	v_mul_f32_e32 v74, v65, v65
	v_fmac_f32_e32 v66, v68, v68
	v_fmac_f32_e32 v67, v70, v70
	v_mul_f32_e32 v75, v73, v73
	v_fmac_f32_e32 v74, v64, v64
	v_add_f32_e32 v66, v66, v67
	v_add_f32_e32 v66, v74, v66
	v_fmac_f32_e32 v75, v72, v72
	v_add_f32_e32 v66, v75, v66
	v_add_f32_e32 v74, v82, v66
	ds_bpermute_b32 v75, v120, v74
	v_cvt_pk_bf16_f32 v66, v68, v69
	v_cvt_pk_bf16_f32 v67, v70, v71
	v_cvt_pk_bf16_f32 v68, v64, v65
	v_lshl_add_u64 v[70:71], s[16:17], 0, v[90:91]
	s_waitcnt lgkmcnt(0)
	v_add_f32_e32 v64, v74, v75
	ds_bpermute_b32 v65, v114, v64
	v_cvt_pk_bf16_f32 v69, v72, v73
	global_store_dwordx4 v[70:71], v[66:69], off
	s_and_saveexec_b64 s[46:47], s[2:3]
	s_cbranch_execz .LBB0_270
	v_lshl_add_u64 v[66:67], v[80:81], 2, s[18:19]
	s_waitcnt lgkmcnt(0)
	v_add_f32_e32 v64, v64, v65
	global_atomic_add_f32 v[66:67], v64, off
.LBB0_270:
	s_or_b64 exec, exec, s[46:47]
	v_add_u32_e32 v64, 0x80, v146
	s_waitcnt lgkmcnt(0)
	v_ashrrev_i32_e32 v65, 31, v64
	v_lshlrev_b64 v[66:67], 11, v[64:65]
	v_lshl_add_u64 v[74:75], v[66:67], 0, v[144:145]
	v_lshl_add_u64 v[76:77], v[74:75], 2, s[52:53]
	s_waitcnt vmcnt(17)
	s_nop 1
	v_mov_b32_e32 v66, v172
	v_mov_b32_e32 v67, v173
	v_mov_b32_e32 v68, v174
	v_mov_b32_e32 v69, v175
	s_waitcnt vmcnt(16)
	s_nop 1
	v_mov_b32_e32 v70, v176
	v_mov_b32_e32 v71, v177
	v_mov_b32_e32 v72, v178
	v_mov_b32_e32 v73, v179
	v_lshlrev_b64 v[74:75], 1, v[74:75]
	v_lshl_add_u64 v[78:79], s[16:17], 0, v[74:75]
	v_or_b32_e32 v74, 0x100, v74
	v_pk_fma_f32 v[68:69], v[62:63], 0.5, v[68:69] op_sel_hi:[1,0,1]
	v_pk_fma_f32 v[66:67], v[60:61], 0.5, v[66:67] op_sel_hi:[1,0,1]
	v_pk_fma_f32 v[72:73], v[58:59], 0.5, v[72:73] op_sel_hi:[1,0,1]
	v_pk_fma_f32 v[70:71], v[56:57], 0.5, v[70:71] op_sel_hi:[1,0,1]
	v_cvt_pk_bf16_f32 v56, v66, v67
	v_cvt_pk_bf16_f32 v57, v68, v69
	v_mul_f32_e32 v67, v67, v67
	v_cvt_pk_bf16_f32 v58, v70, v71
	v_cvt_pk_bf16_f32 v59, v72, v73
	global_store_dwordx4 v[78:79], v[56:59], off
	s_waitcnt vmcnt(16)
	s_nop 1
	v_mov_b32_e32 v56, v180
	v_mov_b32_e32 v57, v181
	v_mov_b32_e32 v58, v182
	v_mov_b32_e32 v59, v183
	s_nop 0
	s_waitcnt vmcnt(15)
	s_nop 1
	v_mov_b32_e32 v60, v184
	v_mov_b32_e32 v61, v185
	v_mov_b32_e32 v62, v186
	v_mov_b32_e32 v63, v187
	v_mul_f32_e32 v69, v69, v69
	v_mul_f32_e32 v71, v71, v71
	v_fmac_f32_e32 v67, v66, v66
	v_fmac_f32_e32 v69, v68, v68
	v_mul_f32_e32 v73, v73, v73
	v_fmac_f32_e32 v71, v70, v70
	v_add_f32_e32 v66, v67, v69
	v_fmac_f32_e32 v73, v72, v72
	v_add_f32_e32 v66, v71, v66
	v_add_f32_e32 v66, v73, v66
	v_pk_fma_f32 v[54:55], v[54:55], 0.5, v[58:59] op_sel_hi:[1,0,1]
	v_pk_fma_f32 v[52:53], v[52:53], 0.5, v[56:57] op_sel_hi:[1,0,1]
	v_pk_fma_f32 v[56:57], v[50:51], 0.5, v[62:63] op_sel_hi:[1,0,1]
	v_pk_fma_f32 v[48:49], v[48:49], 0.5, v[60:61] op_sel_hi:[1,0,1]
	v_mul_f32_e32 v50, v53, v53
	v_mul_f32_e32 v51, v55, v55
	v_mul_f32_e32 v58, v49, v49
	v_fmac_f32_e32 v50, v52, v52
	v_fmac_f32_e32 v51, v54, v54
	v_mul_f32_e32 v59, v57, v57
	v_fmac_f32_e32 v58, v48, v48
	v_add_f32_e32 v50, v50, v51
	v_add_f32_e32 v50, v58, v50
	v_fmac_f32_e32 v59, v56, v56
	v_add_f32_e32 v50, v59, v50
	v_add_f32_e32 v58, v66, v50
	ds_bpermute_b32 v59, v120, v58
	v_cvt_pk_bf16_f32 v50, v52, v53
	v_cvt_pk_bf16_f32 v51, v54, v55
	v_cvt_pk_bf16_f32 v52, v48, v49
	v_lshl_add_u64 v[54:55], s[16:17], 0, v[74:75]
	s_waitcnt lgkmcnt(0)
	v_add_f32_e32 v48, v58, v59
	ds_bpermute_b32 v49, v114, v48
	v_cvt_pk_bf16_f32 v53, v56, v57
	global_store_dwordx4 v[54:55], v[50:53], off
	s_and_saveexec_b64 s[46:47], s[2:3]
	s_cbranch_execz .LBB0_272
	v_lshl_add_u64 v[50:51], v[64:65], 2, s[18:19]
	s_waitcnt lgkmcnt(0)
	v_add_f32_e32 v48, v48, v49
	global_atomic_add_f32 v[50:51], v48, off
; __device__ __forceinline__ unsigned cvt_pk_bf16(float lo, float hi) { unsigned r; asm volatile("v_cvt_pk_bf16_f32 %0, %1, %2" : "=v"(r) : "v"(lo), "v"(hi)); return r; }
;     __device__ __forceinline__ void operator()(const f32x4 (&acc)[2][2][4][2], const Unit& u, int wr, int wc, int fr, int fq) const {
;     ...
;             for (int m = 0; m < 4; ++m) { const int row = row0 + ai * HALF + m * 16; const size_t off = (size_t)row * ldc + col0; float part = 0.f;
; #pragma unroll
;                 for (int bj = 0; bj < 2; ++bj) { const size_t idx = off + bj * HALF;
;                     f32x4 b0, b1;
;                     if constexpr (BASE_BF16) { const u32x4 r = *(const u32x4*)(baseb + idx);
;                         b0 = (f32x4){__builtin_bit_cast(float, r.x << 16), __builtin_bit_cast(float, r.x & 0xffff0000u), __builtin_bit_cast(float, r.y << 16), __builtin_bit_cast(float, r.y & 0xffff0000u)};
;                         b1 = (f32x4){__builtin_bit_cast(float, r.z << 16), __builtin_bit_cast(float, r.z & 0xffff0000u), __builtin_bit_cast(float, r.w << 16), __builtin_bit_cast(float, r.w & 0xffff0000u)}; }
;                     else { b0 = *(const f32x4*)(base + idx); b1 = *(const f32x4*)(base + idx + 4); }
;                     const f32x4 o0 = b0 + acc[ai][bj][m][0] * alpha, o1 = b1 + acc[ai][bj][m][1] * alpha;
;                     if constexpr (WRITE_F32) { *(f32x4*)(out + idx) = o0; *(f32x4*)(out + idx + 4) = o1; }
;                     if constexpr (WRITE_XB) {
;                         part += (o0[0] * o0[0] + o0[1] * o0[1]) + (o0[2] * o0[2] + o0[3] * o0[3]) + (o1[0] * o1[0] + o1[1] * o1[1]) + (o1[2] * o1[2] + o1[3] * o1[3]);
;                         u32x4 w; w.x = cvt_pk_bf16(o0[0], o0[1]); w.y = cvt_pk_bf16(o0[2], o0[3]); w.z = cvt_pk_bf16(o1[0], o1[1]); w.w = cvt_pk_bf16(o1[2], o1[3]);
;                         *(u32x4*)(xb + idx) = w; } }
;                 if constexpr (WRITE_XB) { part += __shfl_xor(part, 16); part += __shfl_xor(part, 32);
;                     if (fq == 0) atomicAdd(ss + row, part); } }
.LBB0_272:
	s_or_b64 exec, exec, s[46:47]
	v_add_u32_e32 v48, 0x90, v146
	s_waitcnt lgkmcnt(0)
	v_ashrrev_i32_e32 v49, 31, v48
	v_lshlrev_b64 v[50:51], 11, v[48:49]
	v_lshl_add_u64 v[58:59], v[50:51], 0, v[144:145]
	v_lshl_add_u64 v[60:61], v[58:59], 2, s[52:53]
	s_waitcnt vmcnt(16)
	s_nop 1
	v_mov_b32_e32 v50, v188
	v_mov_b32_e32 v51, v189
	v_mov_b32_e32 v52, v190
	v_mov_b32_e32 v53, v191
	s_waitcnt vmcnt(15)
	s_nop 1
	v_mov_b32_e32 v54, v192
	v_mov_b32_e32 v55, v193
	v_mov_b32_e32 v56, v194
	v_mov_b32_e32 v57, v195
	v_lshlrev_b64 v[58:59], 1, v[58:59]
	v_lshl_add_u64 v[62:63], s[16:17], 0, v[58:59]
	v_or_b32_e32 v58, 0x100, v58
	v_pk_fma_f32 v[52:53], v[46:47], 0.5, v[52:53] op_sel_hi:[1,0,1]
	v_pk_fma_f32 v[50:51], v[44:45], 0.5, v[50:51] op_sel_hi:[1,0,1]
	v_pk_fma_f32 v[56:57], v[42:43], 0.5, v[56:57] op_sel_hi:[1,0,1]
	v_pk_fma_f32 v[54:55], v[40:41], 0.5, v[54:55] op_sel_hi:[1,0,1]
	v_cvt_pk_bf16_f32 v40, v50, v51
	v_cvt_pk_bf16_f32 v41, v52, v53
	v_mul_f32_e32 v51, v51, v51
	v_cvt_pk_bf16_f32 v42, v54, v55
	v_cvt_pk_bf16_f32 v43, v56, v57
	global_store_dwordx4 v[62:63], v[40:43], off
	s_waitcnt vmcnt(15)
	s_nop 1
	v_mov_b32_e32 v40, v196
	v_mov_b32_e32 v41, v197
	v_mov_b32_e32 v42, v198
	v_mov_b32_e32 v43, v199
	s_nop 0
	s_waitcnt vmcnt(14)
	s_nop 1
	v_mov_b32_e32 v44, v200
	v_mov_b32_e32 v45, v201
	v_mov_b32_e32 v46, v202
	v_mov_b32_e32 v47, v203
	v_mul_f32_e32 v53, v53, v53
	v_mul_f32_e32 v55, v55, v55
	v_fmac_f32_e32 v51, v50, v50
	v_fmac_f32_e32 v53, v52, v52
	v_mul_f32_e32 v57, v57, v57
	v_fmac_f32_e32 v55, v54, v54
	v_add_f32_e32 v50, v51, v53
	v_fmac_f32_e32 v57, v56, v56
	v_add_f32_e32 v50, v55, v50
	v_add_f32_e32 v50, v57, v50
	v_pk_fma_f32 v[38:39], v[38:39], 0.5, v[42:43] op_sel_hi:[1,0,1]
	v_pk_fma_f32 v[36:37], v[36:37], 0.5, v[40:41] op_sel_hi:[1,0,1]
	v_pk_fma_f32 v[40:41], v[34:35], 0.5, v[46:47] op_sel_hi:[1,0,1]
	v_pk_fma_f32 v[32:33], v[32:33], 0.5, v[44:45] op_sel_hi:[1,0,1]
	v_mul_f32_e32 v34, v37, v37
	v_mul_f32_e32 v35, v39, v39
	v_mul_f32_e32 v42, v33, v33
	v_fmac_f32_e32 v34, v36, v36
	v_fmac_f32_e32 v35, v38, v38
	v_mul_f32_e32 v43, v41, v41
	v_fmac_f32_e32 v42, v32, v32
	v_add_f32_e32 v34, v34, v35
	v_add_f32_e32 v34, v42, v34
	v_fmac_f32_e32 v43, v40, v40
	v_add_f32_e32 v34, v43, v34
	v_add_f32_e32 v42, v50, v34
	ds_bpermute_b32 v43, v120, v42
	v_cvt_pk_bf16_f32 v34, v36, v37
	v_cvt_pk_bf16_f32 v35, v38, v39
	v_cvt_pk_bf16_f32 v36, v32, v33
	v_lshl_add_u64 v[38:39], s[16:17], 0, v[58:59]
	s_waitcnt lgkmcnt(0)
	v_add_f32_e32 v32, v42, v43
	ds_bpermute_b32 v33, v114, v32
	v_cvt_pk_bf16_f32 v37, v40, v41
	global_store_dwordx4 v[38:39], v[34:37], off
	s_and_saveexec_b64 s[46:47], s[2:3]
	s_cbranch_execz .LBB0_274
	v_lshl_add_u64 v[34:35], v[48:49], 2, s[18:19]
	s_waitcnt lgkmcnt(0)
	v_add_f32_e32 v32, v32, v33
	global_atomic_add_f32 v[34:35], v32, off
; __device__ __forceinline__ unsigned cvt_pk_bf16(float lo, float hi) { unsigned r; asm volatile("v_cvt_pk_bf16_f32 %0, %1, %2" : "=v"(r) : "v"(lo), "v"(hi)); return r; }
;     __device__ __forceinline__ void operator()(const f32x4 (&acc)[2][2][4][2], const Unit& u, int wr, int wc, int fr, int fq) const {
;     ...
;             for (int m = 0; m < 4; ++m) { const int row = row0 + ai * HALF + m * 16; const size_t off = (size_t)row * ldc + col0; float part = 0.f;
; #pragma unroll
;                 for (int bj = 0; bj < 2; ++bj) { const size_t idx = off + bj * HALF;
;                     f32x4 b0, b1;
;                     if constexpr (BASE_BF16) { const u32x4 r = *(const u32x4*)(baseb + idx);
;                         b0 = (f32x4){__builtin_bit_cast(float, r.x << 16), __builtin_bit_cast(float, r.x & 0xffff0000u), __builtin_bit_cast(float, r.y << 16), __builtin_bit_cast(float, r.y & 0xffff0000u)};
;                         b1 = (f32x4){__builtin_bit_cast(float, r.z << 16), __builtin_bit_cast(float, r.z & 0xffff0000u), __builtin_bit_cast(float, r.w << 16), __builtin_bit_cast(float, r.w & 0xffff0000u)}; }
;                     else { b0 = *(const f32x4*)(base + idx); b1 = *(const f32x4*)(base + idx + 4); }
;                     const f32x4 o0 = b0 + acc[ai][bj][m][0] * alpha, o1 = b1 + acc[ai][bj][m][1] * alpha;
;                     if constexpr (WRITE_F32) { *(f32x4*)(out + idx) = o0; *(f32x4*)(out + idx + 4) = o1; }
;                     if constexpr (WRITE_XB) {
;                         part += (o0[0] * o0[0] + o0[1] * o0[1]) + (o0[2] * o0[2] + o0[3] * o0[3]) + (o1[0] * o1[0] + o1[1] * o1[1]) + (o1[2] * o1[2] + o1[3] * o1[3]);
;                         u32x4 w; w.x = cvt_pk_bf16(o0[0], o0[1]); w.y = cvt_pk_bf16(o0[2], o0[3]); w.z = cvt_pk_bf16(o1[0], o1[1]); w.w = cvt_pk_bf16(o1[2], o1[3]);
;                         *(u32x4*)(xb + idx) = w; } }
;                 if constexpr (WRITE_XB) { part += __shfl_xor(part, 16); part += __shfl_xor(part, 32);
;                     if (fq == 0) atomicAdd(ss + row, part); } }
.LBB0_274:
	s_or_b64 exec, exec, s[46:47]
	v_add_u32_e32 v32, 0xa0, v146
	s_waitcnt lgkmcnt(0)
	v_ashrrev_i32_e32 v33, 31, v32
	v_lshlrev_b64 v[34:35], 11, v[32:33]
	v_lshl_add_u64 v[42:43], v[34:35], 0, v[144:145]
	v_lshl_add_u64 v[44:45], v[42:43], 2, s[52:53]
	s_waitcnt vmcnt(15)
	s_nop 1
	v_mov_b32_e32 v34, v204
	v_mov_b32_e32 v35, v205
	v_mov_b32_e32 v36, v206
	v_mov_b32_e32 v37, v207
	s_waitcnt vmcnt(14)
	s_nop 1
	v_mov_b32_e32 v38, v208
	v_mov_b32_e32 v39, v209
	v_mov_b32_e32 v40, v210
	v_mov_b32_e32 v41, v211
	v_lshlrev_b64 v[42:43], 1, v[42:43]
	v_lshl_add_u64 v[46:47], s[16:17], 0, v[42:43]
	v_or_b32_e32 v42, 0x100, v42
	v_pk_fma_f32 v[36:37], v[30:31], 0.5, v[36:37] op_sel_hi:[1,0,1]
	v_pk_fma_f32 v[34:35], v[28:29], 0.5, v[34:35] op_sel_hi:[1,0,1]
	v_pk_fma_f32 v[40:41], v[26:27], 0.5, v[40:41] op_sel_hi:[1,0,1]
	v_pk_fma_f32 v[38:39], v[24:25], 0.5, v[38:39] op_sel_hi:[1,0,1]
	v_cvt_pk_bf16_f32 v24, v34, v35
	v_cvt_pk_bf16_f32 v25, v36, v37
	v_mul_f32_e32 v35, v35, v35
	v_cvt_pk_bf16_f32 v26, v38, v39
	v_cvt_pk_bf16_f32 v27, v40, v41
	global_store_dwordx4 v[46:47], v[24:27], off
	s_waitcnt vmcnt(14)
	s_nop 1
	v_mov_b32_e32 v24, v212
	v_mov_b32_e32 v25, v213
	v_mov_b32_e32 v26, v214
	v_mov_b32_e32 v27, v215
	s_nop 0
	s_waitcnt vmcnt(13)
	s_nop 1
	v_mov_b32_e32 v28, v220
	v_mov_b32_e32 v29, v221
	v_mov_b32_e32 v30, v222
	v_mov_b32_e32 v31, v223
	v_mul_f32_e32 v37, v37, v37
	v_mul_f32_e32 v39, v39, v39
	v_fmac_f32_e32 v35, v34, v34
	v_fmac_f32_e32 v37, v36, v36
	v_mul_f32_e32 v41, v41, v41
	v_fmac_f32_e32 v39, v38, v38
	v_add_f32_e32 v34, v35, v37
	v_fmac_f32_e32 v41, v40, v40
	v_add_f32_e32 v34, v39, v34
	v_add_f32_e32 v34, v41, v34
	v_pk_fma_f32 v[22:23], v[22:23], 0.5, v[26:27] op_sel_hi:[1,0,1]
	v_pk_fma_f32 v[20:21], v[20:21], 0.5, v[24:25] op_sel_hi:[1,0,1]
	v_pk_fma_f32 v[24:25], v[18:19], 0.5, v[30:31] op_sel_hi:[1,0,1]
	v_pk_fma_f32 v[16:17], v[16:17], 0.5, v[28:29] op_sel_hi:[1,0,1]
	v_mul_f32_e32 v18, v21, v21
	v_mul_f32_e32 v19, v23, v23
	v_mul_f32_e32 v26, v17, v17
	v_fmac_f32_e32 v18, v20, v20
	v_fmac_f32_e32 v19, v22, v22
	v_mul_f32_e32 v27, v25, v25
	v_fmac_f32_e32 v26, v16, v16
	v_add_f32_e32 v18, v18, v19
	v_add_f32_e32 v18, v26, v18
	v_fmac_f32_e32 v27, v24, v24
	v_add_f32_e32 v18, v27, v18
	v_add_f32_e32 v26, v34, v18
	ds_bpermute_b32 v27, v120, v26
	v_cvt_pk_bf16_f32 v18, v20, v21
	v_cvt_pk_bf16_f32 v19, v22, v23
	v_cvt_pk_bf16_f32 v20, v16, v17
	v_lshl_add_u64 v[22:23], s[16:17], 0, v[42:43]
	s_waitcnt lgkmcnt(0)
	v_add_f32_e32 v16, v26, v27
	ds_bpermute_b32 v17, v114, v16
	v_cvt_pk_bf16_f32 v21, v24, v25
	global_store_dwordx4 v[22:23], v[18:21], off
	s_and_saveexec_b64 s[46:47], s[2:3]
	s_cbranch_execz .LBB0_276
	v_lshl_add_u64 v[18:19], v[32:33], 2, s[18:19]
	s_waitcnt lgkmcnt(0)
	v_add_f32_e32 v16, v16, v17
	global_atomic_add_f32 v[18:19], v16, off
.LBB0_276:
	s_or_b64 exec, exec, s[46:47]
	v_add_u32_e32 v16, 0xb0, v146
	s_waitcnt lgkmcnt(0)
	v_ashrrev_i32_e32 v17, 31, v16
	v_lshlrev_b64 v[18:19], 11, v[16:17]
	v_lshl_add_u64 v[26:27], v[18:19], 0, v[144:145]
	v_lshl_add_u64 v[28:29], v[26:27], 2, s[52:53]
	s_waitcnt vmcnt(14)
	s_nop 1
	v_mov_b32_e32 v18, v224
	v_mov_b32_e32 v19, v225
	v_mov_b32_e32 v20, v226
	v_mov_b32_e32 v21, v227
	s_waitcnt vmcnt(13)
	s_nop 1
	v_mov_b32_e32 v22, v228
	v_mov_b32_e32 v23, v229
	v_mov_b32_e32 v24, v230
	v_mov_b32_e32 v25, v231
	v_lshlrev_b64 v[26:27], 1, v[26:27]
	v_lshl_add_u64 v[30:31], s[16:17], 0, v[26:27]
	v_or_b32_e32 v26, 0x100, v26
	v_pk_fma_f32 v[20:21], v[14:15], 0.5, v[20:21] op_sel_hi:[1,0,1]
	v_pk_fma_f32 v[18:19], v[12:13], 0.5, v[18:19] op_sel_hi:[1,0,1]
	v_pk_fma_f32 v[24:25], v[10:11], 0.5, v[24:25] op_sel_hi:[1,0,1]
	v_pk_fma_f32 v[22:23], v[8:9], 0.5, v[22:23] op_sel_hi:[1,0,1]
	v_cvt_pk_bf16_f32 v8, v18, v19
	v_cvt_pk_bf16_f32 v9, v20, v21
	v_mul_f32_e32 v19, v19, v19
	v_cvt_pk_bf16_f32 v10, v22, v23
	v_cvt_pk_bf16_f32 v11, v24, v25
	global_store_dwordx4 v[30:31], v[8:11], off
	s_waitcnt vmcnt(13)
	s_nop 1
	v_mov_b32_e32 v8, v232
	v_mov_b32_e32 v9, v233
	v_mov_b32_e32 v10, v234
	v_mov_b32_e32 v11, v235
	s_nop 0
	s_waitcnt vmcnt(12)
	s_nop 1
	v_mov_b32_e32 v12, v236
	v_mov_b32_e32 v13, v237
	v_mov_b32_e32 v14, v238
	v_mov_b32_e32 v15, v239
	v_mul_f32_e32 v21, v21, v21
	v_mul_f32_e32 v23, v23, v23
	v_fmac_f32_e32 v19, v18, v18
	v_fmac_f32_e32 v21, v20, v20
	v_mul_f32_e32 v25, v25, v25
	v_fmac_f32_e32 v23, v22, v22
	v_add_f32_e32 v18, v19, v21
	v_fmac_f32_e32 v25, v24, v24
	v_add_f32_e32 v18, v23, v18
	v_add_f32_e32 v18, v25, v18
	v_pk_fma_f32 v[6:7], v[6:7], 0.5, v[10:11] op_sel_hi:[1,0,1]
	v_pk_fma_f32 v[4:5], v[4:5], 0.5, v[8:9] op_sel_hi:[1,0,1]
	v_pk_fma_f32 v[8:9], v[2:3], 0.5, v[14:15] op_sel_hi:[1,0,1]
	v_pk_fma_f32 v[0:1], v[0:1], 0.5, v[12:13] op_sel_hi:[1,0,1]
	v_mul_f32_e32 v2, v5, v5
	v_mul_f32_e32 v3, v7, v7
	v_mul_f32_e32 v10, v1, v1
	v_fmac_f32_e32 v2, v4, v4
	v_fmac_f32_e32 v3, v6, v6
	v_mul_f32_e32 v11, v9, v9
	v_fmac_f32_e32 v10, v0, v0
	v_add_f32_e32 v2, v2, v3
	v_add_f32_e32 v2, v10, v2
	v_fmac_f32_e32 v11, v8, v8
	v_add_f32_e32 v2, v11, v2
	v_add_f32_e32 v10, v18, v2
	ds_bpermute_b32 v11, v120, v10
	v_cvt_pk_bf16_f32 v2, v4, v5
	v_cvt_pk_bf16_f32 v3, v6, v7
	v_cvt_pk_bf16_f32 v4, v0, v1
	v_lshl_add_u64 v[6:7], s[16:17], 0, v[26:27]
	s_waitcnt lgkmcnt(0)
	v_add_f32_e32 v0, v10, v11
	ds_bpermute_b32 v1, v114, v0
	v_cvt_pk_bf16_f32 v5, v8, v9
	global_store_dwordx4 v[6:7], v[2:5], off
	s_and_saveexec_b64 s[46:47], s[2:3]
	s_cbranch_execz .LBB0_278
	v_lshl_add_u64 v[2:3], v[16:17], 2, s[18:19]
	s_waitcnt lgkmcnt(0)
	v_add_f32_e32 v0, v0, v1
	global_atomic_add_f32 v[2:3], v0, off

; __device__ __forceinline__ unsigned cvt_pk_bf16(float lo, float hi) { unsigned r; asm volatile("v_cvt_pk_bf16_f32 %0, %1, %2" : "=v"(r) : "v"(lo), "v"(hi)); return r; }
;     __device__ __forceinline__ void operator()(const f32x4 (&acc)[2][2][4][2], const Unit& u, int wr, int wc, int fr, int fq) const {
;     ...
;             for (int m = 0; m < 4; ++m) { const int row = row0 + ai * HALF + m * 16; const size_t off = (size_t)row * ldc + col0; float part = 0.f;
; #pragma unroll
;                 for (int bj = 0; bj < 2; ++bj) { const size_t idx = off + bj * HALF;
;                     f32x4 b0, b1;
;                     if constexpr (BASE_BF16) { const u32x4 r = *(const u32x4*)(baseb + idx);
;                         b0 = (f32x4){__builtin_bit_cast(float, r.x << 16), __builtin_bit_cast(float, r.x & 0xffff0000u), __builtin_bit_cast(float, r.y << 16), __builtin_bit_cast(float, r.y & 0xffff0000u)};
;                         b1 = (f32x4){__builtin_bit_cast(float, r.z << 16), __builtin_bit_cast(float, r.z & 0xffff0000u), __builtin_bit_cast(float, r.w << 16), __builtin_bit_cast(float, r.w & 0xffff0000u)}; }
;                     else { b0 = *(const f32x4*)(base + idx); b1 = *(const f32x4*)(base + idx + 4); }
;                     const f32x4 o0 = b0 + acc[ai][bj][m][0] * alpha, o1 = b1 + acc[ai][bj][m][1] * alpha;
;                     if constexpr (WRITE_F32) { *(f32x4*)(out + idx) = o0; *(f32x4*)(out + idx + 4) = o1; }
;                     if constexpr (WRITE_XB) {
;                         part += (o0[0] * o0[0] + o0[1] * o0[1]) + (o0[2] * o0[2] + o0[3] * o0[3]) + (o1[0] * o1[0] + o1[1] * o1[1]) + (o1[2] * o1[2] + o1[3] * o1[3]);
;                         u32x4 w; w.x = cvt_pk_bf16(o0[0], o0[1]); w.y = cvt_pk_bf16(o0[2], o0[3]); w.z = cvt_pk_bf16(o1[0], o1[1]); w.w = cvt_pk_bf16(o1[2], o1[3]);
;                         *(u32x4*)(xb + idx) = w; } }
;                 if constexpr (WRITE_XB) { part += __shfl_xor(part, 16); part += __shfl_xor(part, 32);
;                     if (fq == 0) atomicAdd(ss + row, part); } }
.LBB0_689:
	s_or_b64 exec, exec, s[42:43]
	v_or_b32_e32 v112, 16, v146
	s_waitcnt lgkmcnt(0)
	v_ashrrev_i32_e32 v113, 31, v112
	v_lshlrev_b64 v[116:117], 11, v[112:113]
	v_lshl_add_u64 v[116:117], v[116:117], 0, v[144:145]
	v_lshlrev_b64 v[122:123], 1, v[116:117]
	v_lshl_add_u64 v[116:117], s[14:15], 0, v[122:123]
	s_waitcnt vmcnt(16)
	s_nop 1
	v_mov_b32_e32 v116, v180
	v_mov_b32_e32 v117, v181
	v_mov_b32_e32 v118, v182
	v_mov_b32_e32 v119, v183
	v_lshl_add_u64 v[124:125], s[16:17], 0, v[122:123]
	v_or_b32_e32 v122, 0x100, v122
	v_lshl_add_u64 v[126:127], s[14:15], 0, v[122:123]
	v_lshlrev_b32_e32 v156, 16, v116
	v_and_b32_e32 v157, 0xffff0000, v116
	v_lshlrev_b32_e32 v116, 16, v117
	v_and_b32_e32 v117, 0xffff0000, v117
	v_lshlrev_b32_e32 v158, 16, v118
	v_and_b32_e32 v159, 0xffff0000, v118
	v_lshlrev_b32_e32 v118, 16, v119
	v_and_b32_e32 v119, 0xffff0000, v119
	v_pk_add_f32 v[116:117], v[110:111], v[116:117]
	v_pk_add_f32 v[156:157], v[108:109], v[156:157]
	v_pk_add_f32 v[118:119], v[106:107], v[118:119]
	v_pk_add_f32 v[158:159], v[104:105], v[158:159]
	v_cvt_pk_bf16_f32 v104, v156, v157
	v_cvt_pk_bf16_f32 v105, v116, v117
	v_mul_f32_e32 v115, v157, v157
	v_cvt_pk_bf16_f32 v106, v158, v159
	v_cvt_pk_bf16_f32 v107, v118, v119
	s_waitcnt vmcnt(15)
	s_nop 1
	v_mov_b32_e32 v108, v184
	v_mov_b32_e32 v109, v185
	v_mov_b32_e32 v110, v186
	v_mov_b32_e32 v111, v187
	v_mul_f32_e32 v117, v117, v117
	v_mul_f32_e32 v121, v159, v159
	v_fmac_f32_e32 v115, v156, v156
	v_fmac_f32_e32 v117, v116, v116
	v_mul_f32_e32 v119, v119, v119
	v_fmac_f32_e32 v121, v158, v158
	v_add_f32_e32 v115, v115, v117
	v_fmac_f32_e32 v119, v118, v118
	v_add_f32_e32 v115, v121, v115
	v_add_f32_e32 v115, v119, v115
	global_store_dwordx4 v[124:125], v[104:107], off
	v_lshlrev_b32_e32 v116, 16, v108
	v_and_b32_e32 v117, 0xffff0000, v108
	v_lshlrev_b32_e32 v108, 16, v109
	v_and_b32_e32 v109, 0xffff0000, v109
	v_lshlrev_b32_e32 v118, 16, v110
	v_and_b32_e32 v119, 0xffff0000, v110
	v_lshlrev_b32_e32 v110, 16, v111
	v_and_b32_e32 v111, 0xffff0000, v111
	v_pk_add_f32 v[102:103], v[102:103], v[108:109]
	v_pk_add_f32 v[100:101], v[100:101], v[116:117]
	v_pk_add_f32 v[108:109], v[98:99], v[110:111]
	v_pk_add_f32 v[110:111], v[96:97], v[118:119]
	v_mul_f32_e32 v96, v101, v101
	v_mul_f32_e32 v97, v103, v103
	v_mul_f32_e32 v98, v111, v111
	v_fmac_f32_e32 v96, v100, v100
	v_fmac_f32_e32 v97, v102, v102
	v_mul_f32_e32 v99, v109, v109
	v_fmac_f32_e32 v98, v110, v110
	v_add_f32_e32 v96, v96, v97
	v_add_f32_e32 v96, v98, v96
	v_fmac_f32_e32 v99, v108, v108
	v_add_f32_e32 v96, v99, v96
	v_add_f32_e32 v96, v115, v96
	ds_bpermute_b32 v97, v120, v96
	v_cvt_pk_bf16_f32 v98, v100, v101
	v_cvt_pk_bf16_f32 v99, v102, v103
	v_lshl_add_u64 v[102:103], s[16:17], 0, v[122:123]
	v_cvt_pk_bf16_f32 v100, v110, v111
	s_waitcnt lgkmcnt(0)
	v_add_f32_e32 v96, v96, v97
	ds_bpermute_b32 v97, v114, v96
	v_cvt_pk_bf16_f32 v101, v108, v109
	global_store_dwordx4 v[102:103], v[98:101], off
	s_and_saveexec_b64 s[42:43], s[2:3]
	s_cbranch_execz .LBB0_691
	v_lshl_add_u64 v[98:99], v[112:113], 2, s[18:19]
	s_waitcnt lgkmcnt(0)
	v_add_f32_e32 v96, v96, v97
	global_atomic_add_f32 v[98:99], v96, off
.LBB0_691:
	s_or_b64 exec, exec, s[42:43]
	v_or_b32_e32 v96, 32, v146
	s_waitcnt lgkmcnt(0)
	v_ashrrev_i32_e32 v97, 31, v96
	v_lshlrev_b64 v[98:99], 11, v[96:97]
	v_lshl_add_u64 v[98:99], v[98:99], 0, v[144:145]
	v_lshlrev_b64 v[102:103], 1, v[98:99]
	v_lshl_add_u64 v[98:99], s[14:15], 0, v[102:103]
	s_waitcnt vmcnt(17)
	s_nop 1
	v_mov_b32_e32 v98, v188
	v_mov_b32_e32 v99, v189
	v_mov_b32_e32 v100, v190
	v_mov_b32_e32 v101, v191
	v_lshl_add_u64 v[104:105], s[16:17], 0, v[102:103]
	v_or_b32_e32 v102, 0x100, v102
	v_lshl_add_u64 v[106:107], s[14:15], 0, v[102:103]
	v_lshlrev_b32_e32 v108, 16, v98
	v_and_b32_e32 v109, 0xffff0000, v98
	v_lshlrev_b32_e32 v98, 16, v99
	v_and_b32_e32 v99, 0xffff0000, v99
	v_lshlrev_b32_e32 v110, 16, v100
	v_and_b32_e32 v111, 0xffff0000, v100
	v_lshlrev_b32_e32 v100, 16, v101
	v_and_b32_e32 v101, 0xffff0000, v101
	v_pk_add_f32 v[98:99], v[94:95], v[98:99]
	v_pk_add_f32 v[108:109], v[92:93], v[108:109]
	v_pk_add_f32 v[100:101], v[90:91], v[100:101]
	v_pk_add_f32 v[110:111], v[88:89], v[110:111]
	v_cvt_pk_bf16_f32 v88, v108, v109
	v_cvt_pk_bf16_f32 v89, v98, v99
	v_mul_f32_e32 v99, v99, v99
	v_cvt_pk_bf16_f32 v90, v110, v111
	v_cvt_pk_bf16_f32 v91, v100, v101
	s_waitcnt vmcnt(16)
	s_nop 1
	v_mov_b32_e32 v92, v192
	v_mov_b32_e32 v93, v193
	v_mov_b32_e32 v94, v194
	v_mov_b32_e32 v95, v195
	v_mul_f32_e32 v106, v109, v109
	v_mul_f32_e32 v107, v111, v111
	v_fmac_f32_e32 v106, v108, v108
	v_fmac_f32_e32 v99, v98, v98
	v_mul_f32_e32 v101, v101, v101
	v_fmac_f32_e32 v107, v110, v110
	v_add_f32_e32 v98, v106, v99
	v_fmac_f32_e32 v101, v100, v100
	v_add_f32_e32 v98, v107, v98
	v_add_f32_e32 v106, v101, v98
	global_store_dwordx4 v[104:105], v[88:91], off
	v_lshlrev_b32_e32 v98, 16, v92
	v_and_b32_e32 v99, 0xffff0000, v92
	v_lshlrev_b32_e32 v92, 16, v93
	v_and_b32_e32 v93, 0xffff0000, v93
	v_lshlrev_b32_e32 v100, 16, v94
	v_and_b32_e32 v101, 0xffff0000, v94
	v_lshlrev_b32_e32 v94, 16, v95
	v_and_b32_e32 v95, 0xffff0000, v95
	v_pk_add_f32 v[86:87], v[86:87], v[92:93]
	v_pk_add_f32 v[84:85], v[84:85], v[98:99]
	v_pk_add_f32 v[92:93], v[82:83], v[94:95]
	v_pk_add_f32 v[94:95], v[80:81], v[100:101]
	v_mul_f32_e32 v80, v85, v85
	v_mul_f32_e32 v81, v87, v87
	v_mul_f32_e32 v82, v95, v95
	v_fmac_f32_e32 v80, v84, v84
	v_fmac_f32_e32 v81, v86, v86
	v_mul_f32_e32 v83, v93, v93
	v_fmac_f32_e32 v82, v94, v94
	v_add_f32_e32 v80, v80, v81
	v_add_f32_e32 v80, v82, v80
	v_fmac_f32_e32 v83, v92, v92
	v_add_f32_e32 v80, v83, v80
	v_add_f32_e32 v80, v106, v80
	ds_bpermute_b32 v81, v120, v80
	v_cvt_pk_bf16_f32 v82, v84, v85
	v_cvt_pk_bf16_f32 v83, v86, v87
	v_lshl_add_u64 v[86:87], s[16:17], 0, v[102:103]
	v_cvt_pk_bf16_f32 v84, v94, v95
	s_waitcnt lgkmcnt(0)
	v_add_f32_e32 v80, v80, v81
	ds_bpermute_b32 v81, v114, v80
	v_cvt_pk_bf16_f32 v85, v92, v93
	global_store_dwordx4 v[86:87], v[82:85], off
	s_and_saveexec_b64 s[42:43], s[2:3]
	s_cbranch_execz .LBB0_693
	v_lshl_add_u64 v[82:83], v[96:97], 2, s[18:19]
	s_waitcnt lgkmcnt(0)
	v_add_f32_e32 v80, v80, v81
	global_atomic_add_f32 v[82:83], v80, off
; __device__ __forceinline__ unsigned cvt_pk_bf16(float lo, float hi) { unsigned r; asm volatile("v_cvt_pk_bf16_f32 %0, %1, %2" : "=v"(r) : "v"(lo), "v"(hi)); return r; }
;     __device__ __forceinline__ void operator()(const f32x4 (&acc)[2][2][4][2], const Unit& u, int wr, int wc, int fr, int fq) const {
;     ...
;             for (int m = 0; m < 4; ++m) { const int row = row0 + ai * HALF + m * 16; const size_t off = (size_t)row * ldc + col0; float part = 0.f;
; #pragma unroll
;                 for (int bj = 0; bj < 2; ++bj) { const size_t idx = off + bj * HALF;
;                     f32x4 b0, b1;
;                     if constexpr (BASE_BF16) { const u32x4 r = *(const u32x4*)(baseb + idx);
;                         b0 = (f32x4){__builtin_bit_cast(float, r.x << 16), __builtin_bit_cast(float, r.x & 0xffff0000u), __builtin_bit_cast(float, r.y << 16), __builtin_bit_cast(float, r.y & 0xffff0000u)};
;                         b1 = (f32x4){__builtin_bit_cast(float, r.z << 16), __builtin_bit_cast(float, r.z & 0xffff0000u), __builtin_bit_cast(float, r.w << 16), __builtin_bit_cast(float, r.w & 0xffff0000u)}; }
;                     else { b0 = *(const f32x4*)(base + idx); b1 = *(const f32x4*)(base + idx + 4); }
;                     const f32x4 o0 = b0 + acc[ai][bj][m][0] * alpha, o1 = b1 + acc[ai][bj][m][1] * alpha;
;                     if constexpr (WRITE_F32) { *(f32x4*)(out + idx) = o0; *(f32x4*)(out + idx + 4) = o1; }
;                     if constexpr (WRITE_XB) {
;                         part += (o0[0] * o0[0] + o0[1] * o0[1]) + (o0[2] * o0[2] + o0[3] * o0[3]) + (o1[0] * o1[0] + o1[1] * o1[1]) + (o1[2] * o1[2] + o1[3] * o1[3]);
;                         u32x4 w; w.x = cvt_pk_bf16(o0[0], o0[1]); w.y = cvt_pk_bf16(o0[2], o0[3]); w.z = cvt_pk_bf16(o1[0], o1[1]); w.w = cvt_pk_bf16(o1[2], o1[3]);
;                         *(u32x4*)(xb + idx) = w; } }
;                 if constexpr (WRITE_XB) { part += __shfl_xor(part, 16); part += __shfl_xor(part, 32);
;                     if (fq == 0) atomicAdd(ss + row, part); } }
.LBB0_693:
	s_or_b64 exec, exec, s[42:43]
	v_or_b32_e32 v80, 48, v146
	s_waitcnt lgkmcnt(0)
	v_ashrrev_i32_e32 v81, 31, v80
	v_lshlrev_b64 v[82:83], 11, v[80:81]
	v_lshl_add_u64 v[82:83], v[82:83], 0, v[144:145]
	v_lshlrev_b64 v[86:87], 1, v[82:83]
	v_lshl_add_u64 v[82:83], s[14:15], 0, v[86:87]
	s_waitcnt vmcnt(18)
	s_nop 1
	v_mov_b32_e32 v82, v196
	v_mov_b32_e32 v83, v197
	v_mov_b32_e32 v84, v198
	v_mov_b32_e32 v85, v199
	v_lshl_add_u64 v[88:89], s[16:17], 0, v[86:87]
	v_or_b32_e32 v86, 0x100, v86
	v_lshl_add_u64 v[90:91], s[14:15], 0, v[86:87]
	v_lshlrev_b32_e32 v92, 16, v82
	v_and_b32_e32 v93, 0xffff0000, v82
	v_lshlrev_b32_e32 v82, 16, v83
	v_and_b32_e32 v83, 0xffff0000, v83
	v_lshlrev_b32_e32 v94, 16, v84
	v_and_b32_e32 v95, 0xffff0000, v84
	v_lshlrev_b32_e32 v84, 16, v85
	v_and_b32_e32 v85, 0xffff0000, v85
	v_pk_add_f32 v[82:83], v[78:79], v[82:83]
	v_pk_add_f32 v[92:93], v[76:77], v[92:93]
	v_pk_add_f32 v[84:85], v[74:75], v[84:85]
	v_pk_add_f32 v[94:95], v[72:73], v[94:95]
	v_cvt_pk_bf16_f32 v72, v92, v93
	v_cvt_pk_bf16_f32 v73, v82, v83
	v_mul_f32_e32 v83, v83, v83
	v_cvt_pk_bf16_f32 v74, v94, v95
	v_cvt_pk_bf16_f32 v75, v84, v85
	s_waitcnt vmcnt(17)
	s_nop 1
	v_mov_b32_e32 v76, v200
	v_mov_b32_e32 v77, v201
	v_mov_b32_e32 v78, v202
	v_mov_b32_e32 v79, v203
	v_mul_f32_e32 v90, v93, v93
	v_mul_f32_e32 v91, v95, v95
	v_fmac_f32_e32 v90, v92, v92
	v_fmac_f32_e32 v83, v82, v82
	v_mul_f32_e32 v85, v85, v85
	v_fmac_f32_e32 v91, v94, v94
	v_add_f32_e32 v82, v90, v83
	v_fmac_f32_e32 v85, v84, v84
	v_add_f32_e32 v82, v91, v82
	v_add_f32_e32 v90, v85, v82
	global_store_dwordx4 v[88:89], v[72:75], off
	v_lshlrev_b32_e32 v82, 16, v76
	v_and_b32_e32 v83, 0xffff0000, v76
	v_lshlrev_b32_e32 v76, 16, v77
	v_and_b32_e32 v77, 0xffff0000, v77
	v_lshlrev_b32_e32 v84, 16, v78
	v_and_b32_e32 v85, 0xffff0000, v78
	v_lshlrev_b32_e32 v78, 16, v79
	v_and_b32_e32 v79, 0xffff0000, v79
	v_pk_add_f32 v[70:71], v[70:71], v[76:77]
	v_pk_add_f32 v[68:69], v[68:69], v[82:83]
	v_pk_add_f32 v[76:77], v[66:67], v[78:79]
	v_pk_add_f32 v[78:79], v[64:65], v[84:85]
	v_mul_f32_e32 v64, v69, v69
	v_mul_f32_e32 v65, v71, v71
	v_mul_f32_e32 v66, v79, v79
	v_fmac_f32_e32 v64, v68, v68
	v_fmac_f32_e32 v65, v70, v70
	v_mul_f32_e32 v67, v77, v77
	v_fmac_f32_e32 v66, v78, v78
	v_add_f32_e32 v64, v64, v65
	v_add_f32_e32 v64, v66, v64
	v_fmac_f32_e32 v67, v76, v76
	v_add_f32_e32 v64, v67, v64
	v_add_f32_e32 v64, v90, v64
	ds_bpermute_b32 v65, v120, v64
	v_cvt_pk_bf16_f32 v66, v68, v69
	v_cvt_pk_bf16_f32 v67, v70, v71
	v_lshl_add_u64 v[70:71], s[16:17], 0, v[86:87]
	v_cvt_pk_bf16_f32 v68, v78, v79
	s_waitcnt lgkmcnt(0)
	v_add_f32_e32 v64, v64, v65
	ds_bpermute_b32 v65, v114, v64
	v_cvt_pk_bf16_f32 v69, v76, v77
	global_store_dwordx4 v[70:71], v[66:69], off
	s_and_saveexec_b64 s[42:43], s[2:3]
	s_cbranch_execz .LBB0_695
	v_lshl_add_u64 v[66:67], v[80:81], 2, s[18:19]
	s_waitcnt lgkmcnt(0)
	v_add_f32_e32 v64, v64, v65
	global_atomic_add_f32 v[66:67], v64, off
.LBB0_695:
	s_or_b64 exec, exec, s[42:43]
	v_add_u32_e32 v64, 0x80, v146
	s_waitcnt lgkmcnt(0)
	v_ashrrev_i32_e32 v65, 31, v64
	v_lshlrev_b64 v[66:67], 11, v[64:65]
	v_lshl_add_u64 v[66:67], v[66:67], 0, v[144:145]
	v_lshlrev_b64 v[70:71], 1, v[66:67]
	v_lshl_add_u64 v[66:67], s[14:15], 0, v[70:71]
	s_waitcnt vmcnt(19)
	s_nop 1
	v_mov_b32_e32 v66, v204
	v_mov_b32_e32 v67, v205
	v_mov_b32_e32 v68, v206
	v_mov_b32_e32 v69, v207
	v_lshl_add_u64 v[72:73], s[16:17], 0, v[70:71]
	v_or_b32_e32 v70, 0x100, v70
	v_lshl_add_u64 v[74:75], s[14:15], 0, v[70:71]
	v_lshlrev_b32_e32 v76, 16, v66
	v_and_b32_e32 v77, 0xffff0000, v66
	v_lshlrev_b32_e32 v66, 16, v67
	v_and_b32_e32 v67, 0xffff0000, v67
	v_lshlrev_b32_e32 v78, 16, v68
	v_and_b32_e32 v79, 0xffff0000, v68
	v_lshlrev_b32_e32 v68, 16, v69
	v_and_b32_e32 v69, 0xffff0000, v69
	v_pk_add_f32 v[66:67], v[62:63], v[66:67]
	v_pk_add_f32 v[76:77], v[60:61], v[76:77]
	v_pk_add_f32 v[68:69], v[58:59], v[68:69]
	v_pk_add_f32 v[78:79], v[56:57], v[78:79]
	v_cvt_pk_bf16_f32 v56, v76, v77
	v_cvt_pk_bf16_f32 v57, v66, v67
	v_mul_f32_e32 v67, v67, v67
	v_cvt_pk_bf16_f32 v58, v78, v79
	v_cvt_pk_bf16_f32 v59, v68, v69
	s_waitcnt vmcnt(18)
	s_nop 1
	v_mov_b32_e32 v60, v208
	v_mov_b32_e32 v61, v209
	v_mov_b32_e32 v62, v210
	v_mov_b32_e32 v63, v211
	v_mul_f32_e32 v74, v77, v77
	v_mul_f32_e32 v75, v79, v79
	v_fmac_f32_e32 v74, v76, v76
	v_fmac_f32_e32 v67, v66, v66
	v_mul_f32_e32 v69, v69, v69
	v_fmac_f32_e32 v75, v78, v78
	v_add_f32_e32 v66, v74, v67
	v_fmac_f32_e32 v69, v68, v68
	v_add_f32_e32 v66, v75, v66
	v_add_f32_e32 v74, v69, v66
	global_store_dwordx4 v[72:73], v[56:59], off
	v_lshlrev_b32_e32 v66, 16, v60
	v_and_b32_e32 v67, 0xffff0000, v60
	v_lshlrev_b32_e32 v60, 16, v61
	v_and_b32_e32 v61, 0xffff0000, v61
	v_lshlrev_b32_e32 v68, 16, v62
	v_and_b32_e32 v69, 0xffff0000, v62
	v_lshlrev_b32_e32 v62, 16, v63
	v_and_b32_e32 v63, 0xffff0000, v63
	v_pk_add_f32 v[54:55], v[54:55], v[60:61]
	v_pk_add_f32 v[52:53], v[52:53], v[66:67]
	v_pk_add_f32 v[60:61], v[50:51], v[62:63]
	v_pk_add_f32 v[62:63], v[48:49], v[68:69]
	v_mul_f32_e32 v48, v53, v53
	v_mul_f32_e32 v49, v55, v55
	v_mul_f32_e32 v50, v63, v63
	v_fmac_f32_e32 v48, v52, v52
	v_fmac_f32_e32 v49, v54, v54
	v_mul_f32_e32 v51, v61, v61
	v_fmac_f32_e32 v50, v62, v62
	v_add_f32_e32 v48, v48, v49
	v_add_f32_e32 v48, v50, v48
	v_fmac_f32_e32 v51, v60, v60
	v_add_f32_e32 v48, v51, v48
	v_add_f32_e32 v48, v74, v48
	ds_bpermute_b32 v49, v120, v48
	v_cvt_pk_bf16_f32 v50, v52, v53
	v_cvt_pk_bf16_f32 v51, v54, v55
	v_lshl_add_u64 v[54:55], s[16:17], 0, v[70:71]
	v_cvt_pk_bf16_f32 v52, v62, v63
	s_waitcnt lgkmcnt(0)
	v_add_f32_e32 v48, v48, v49
	ds_bpermute_b32 v49, v114, v48
	v_cvt_pk_bf16_f32 v53, v60, v61
	global_store_dwordx4 v[54:55], v[50:53], off
	s_and_saveexec_b64 s[42:43], s[2:3]
	s_cbranch_execz .LBB0_697
	v_lshl_add_u64 v[50:51], v[64:65], 2, s[18:19]
	s_waitcnt lgkmcnt(0)
	v_add_f32_e32 v48, v48, v49
	global_atomic_add_f32 v[50:51], v48, off
; __device__ __forceinline__ unsigned cvt_pk_bf16(float lo, float hi) { unsigned r; asm volatile("v_cvt_pk_bf16_f32 %0, %1, %2" : "=v"(r) : "v"(lo), "v"(hi)); return r; }
;     __device__ __forceinline__ void operator()(const f32x4 (&acc)[2][2][4][2], const Unit& u, int wr, int wc, int fr, int fq) const {
;     ...
;             for (int m = 0; m < 4; ++m) { const int row = row0 + ai * HALF + m * 16; const size_t off = (size_t)row * ldc + col0; float part = 0.f;
; #pragma unroll
;                 for (int bj = 0; bj < 2; ++bj) { const size_t idx = off + bj * HALF;
;                     f32x4 b0, b1;
;                     if constexpr (BASE_BF16) { const u32x4 r = *(const u32x4*)(baseb + idx);
;                         b0 = (f32x4){__builtin_bit_cast(float, r.x << 16), __builtin_bit_cast(float, r.x & 0xffff0000u), __builtin_bit_cast(float, r.y << 16), __builtin_bit_cast(float, r.y & 0xffff0000u)};
;                         b1 = (f32x4){__builtin_bit_cast(float, r.z << 16), __builtin_bit_cast(float, r.z & 0xffff0000u), __builtin_bit_cast(float, r.w << 16), __builtin_bit_cast(float, r.w & 0xffff0000u)}; }
;                     else { b0 = *(const f32x4*)(base + idx); b1 = *(const f32x4*)(base + idx + 4); }
;                     const f32x4 o0 = b0 + acc[ai][bj][m][0] * alpha, o1 = b1 + acc[ai][bj][m][1] * alpha;
;                     if constexpr (WRITE_F32) { *(f32x4*)(out + idx) = o0; *(f32x4*)(out + idx + 4) = o1; }
;                     if constexpr (WRITE_XB) {
;                         part += (o0[0] * o0[0] + o0[1] * o0[1]) + (o0[2] * o0[2] + o0[3] * o0[3]) + (o1[0] * o1[0] + o1[1] * o1[1]) + (o1[2] * o1[2] + o1[3] * o1[3]);
;                         u32x4 w; w.x = cvt_pk_bf16(o0[0], o0[1]); w.y = cvt_pk_bf16(o0[2], o0[3]); w.z = cvt_pk_bf16(o1[0], o1[1]); w.w = cvt_pk_bf16(o1[2], o1[3]);
;                         *(u32x4*)(xb + idx) = w; } }
;                 if constexpr (WRITE_XB) { part += __shfl_xor(part, 16); part += __shfl_xor(part, 32);
;                     if (fq == 0) atomicAdd(ss + row, part); } }
.LBB0_697:
	s_or_b64 exec, exec, s[42:43]
	v_add_u32_e32 v48, 0x90, v146
	s_waitcnt lgkmcnt(0)
	v_ashrrev_i32_e32 v49, 31, v48
	v_lshlrev_b64 v[50:51], 11, v[48:49]
	v_lshl_add_u64 v[50:51], v[50:51], 0, v[144:145]
	v_lshlrev_b64 v[54:55], 1, v[50:51]
	v_lshl_add_u64 v[50:51], s[14:15], 0, v[54:55]
	s_waitcnt vmcnt(20)
	s_nop 1
	v_mov_b32_e32 v50, v212
	v_mov_b32_e32 v51, v213
	v_mov_b32_e32 v52, v214
	v_mov_b32_e32 v53, v215
	v_lshl_add_u64 v[56:57], s[16:17], 0, v[54:55]
	v_or_b32_e32 v54, 0x100, v54
	v_lshl_add_u64 v[58:59], s[14:15], 0, v[54:55]
	v_lshlrev_b32_e32 v60, 16, v50
	v_and_b32_e32 v61, 0xffff0000, v50
	v_lshlrev_b32_e32 v50, 16, v51
	v_and_b32_e32 v51, 0xffff0000, v51
	v_lshlrev_b32_e32 v62, 16, v52
	v_and_b32_e32 v63, 0xffff0000, v52
	v_lshlrev_b32_e32 v52, 16, v53
	v_and_b32_e32 v53, 0xffff0000, v53
	v_pk_add_f32 v[50:51], v[46:47], v[50:51]
	v_pk_add_f32 v[60:61], v[44:45], v[60:61]
	v_pk_add_f32 v[52:53], v[42:43], v[52:53]
	v_pk_add_f32 v[62:63], v[40:41], v[62:63]
	v_cvt_pk_bf16_f32 v40, v60, v61
	v_cvt_pk_bf16_f32 v41, v50, v51
	v_mul_f32_e32 v51, v51, v51
	v_cvt_pk_bf16_f32 v42, v62, v63
	v_cvt_pk_bf16_f32 v43, v52, v53
	s_waitcnt vmcnt(19)
	s_nop 1
	v_mov_b32_e32 v44, v220
	v_mov_b32_e32 v45, v221
	v_mov_b32_e32 v46, v222
	v_mov_b32_e32 v47, v223
	v_mul_f32_e32 v58, v61, v61
	v_mul_f32_e32 v59, v63, v63
	v_fmac_f32_e32 v58, v60, v60
	v_fmac_f32_e32 v51, v50, v50
	v_mul_f32_e32 v53, v53, v53
	v_fmac_f32_e32 v59, v62, v62
	v_add_f32_e32 v50, v58, v51
	v_fmac_f32_e32 v53, v52, v52
	v_add_f32_e32 v50, v59, v50
	v_add_f32_e32 v58, v53, v50
	global_store_dwordx4 v[56:57], v[40:43], off
	v_lshlrev_b32_e32 v50, 16, v44
	v_and_b32_e32 v51, 0xffff0000, v44
	v_lshlrev_b32_e32 v44, 16, v45
	v_and_b32_e32 v45, 0xffff0000, v45
	v_lshlrev_b32_e32 v52, 16, v46
	v_and_b32_e32 v53, 0xffff0000, v46
	v_lshlrev_b32_e32 v46, 16, v47
	v_and_b32_e32 v47, 0xffff0000, v47
	v_pk_add_f32 v[38:39], v[38:39], v[44:45]
	v_pk_add_f32 v[36:37], v[36:37], v[50:51]
	v_pk_add_f32 v[44:45], v[34:35], v[46:47]
	v_pk_add_f32 v[46:47], v[32:33], v[52:53]
	v_mul_f32_e32 v32, v37, v37
	v_mul_f32_e32 v33, v39, v39
	v_mul_f32_e32 v34, v47, v47
	v_fmac_f32_e32 v32, v36, v36
	v_fmac_f32_e32 v33, v38, v38
	v_mul_f32_e32 v35, v45, v45
	v_fmac_f32_e32 v34, v46, v46
	v_add_f32_e32 v32, v32, v33
	v_add_f32_e32 v32, v34, v32
	v_fmac_f32_e32 v35, v44, v44
	v_add_f32_e32 v32, v35, v32
	v_add_f32_e32 v32, v58, v32
	ds_bpermute_b32 v33, v120, v32
	v_cvt_pk_bf16_f32 v34, v36, v37
	v_cvt_pk_bf16_f32 v35, v38, v39
	v_lshl_add_u64 v[38:39], s[16:17], 0, v[54:55]
	v_cvt_pk_bf16_f32 v36, v46, v47
	s_waitcnt lgkmcnt(0)
	v_add_f32_e32 v32, v32, v33
	ds_bpermute_b32 v33, v114, v32
	v_cvt_pk_bf16_f32 v37, v44, v45
	global_store_dwordx4 v[38:39], v[34:37], off
	s_and_saveexec_b64 s[42:43], s[2:3]
	s_cbranch_execz .LBB0_699
	v_lshl_add_u64 v[34:35], v[48:49], 2, s[18:19]
	s_waitcnt lgkmcnt(0)
	v_add_f32_e32 v32, v32, v33
	global_atomic_add_f32 v[34:35], v32, off
; __device__ __forceinline__ unsigned cvt_pk_bf16(float lo, float hi) { unsigned r; asm volatile("v_cvt_pk_bf16_f32 %0, %1, %2" : "=v"(r) : "v"(lo), "v"(hi)); return r; }
;     __device__ __forceinline__ void operator()(const f32x4 (&acc)[2][2][4][2], const Unit& u, int wr, int wc, int fr, int fq) const {
;     ...
;             for (int m = 0; m < 4; ++m) { const int row = row0 + ai * HALF + m * 16; const size_t off = (size_t)row * ldc + col0; float part = 0.f;
; #pragma unroll
;                 for (int bj = 0; bj < 2; ++bj) { const size_t idx = off + bj * HALF;
;                     f32x4 b0, b1;
;                     if constexpr (BASE_BF16) { const u32x4 r = *(const u32x4*)(baseb + idx);
;                         b0 = (f32x4){__builtin_bit_cast(float, r.x << 16), __builtin_bit_cast(float, r.x & 0xffff0000u), __builtin_bit_cast(float, r.y << 16), __builtin_bit_cast(float, r.y & 0xffff0000u)};
;                         b1 = (f32x4){__builtin_bit_cast(float, r.z << 16), __builtin_bit_cast(float, r.z & 0xffff0000u), __builtin_bit_cast(float, r.w << 16), __builtin_bit_cast(float, r.w & 0xffff0000u)}; }
;                     else { b0 = *(const f32x4*)(base + idx); b1 = *(const f32x4*)(base + idx + 4); }
;                     const f32x4 o0 = b0 + acc[ai][bj][m][0] * alpha, o1 = b1 + acc[ai][bj][m][1] * alpha;
;                     if constexpr (WRITE_F32) { *(f32x4*)(out + idx) = o0; *(f32x4*)(out + idx + 4) = o1; }
;                     if constexpr (WRITE_XB) {
;                         part += (o0[0] * o0[0] + o0[1] * o0[1]) + (o0[2] * o0[2] + o0[3] * o0[3]) + (o1[0] * o1[0] + o1[1] * o1[1]) + (o1[2] * o1[2] + o1[3] * o1[3]);
;                         u32x4 w; w.x = cvt_pk_bf16(o0[0], o0[1]); w.y = cvt_pk_bf16(o0[2], o0[3]); w.z = cvt_pk_bf16(o1[0], o1[1]); w.w = cvt_pk_bf16(o1[2], o1[3]);
;                         *(u32x4*)(xb + idx) = w; } }
;                 if constexpr (WRITE_XB) { part += __shfl_xor(part, 16); part += __shfl_xor(part, 32);
;                     if (fq == 0) atomicAdd(ss + row, part); } }
.LBB0_699:
	s_or_b64 exec, exec, s[42:43]
	v_add_u32_e32 v32, 0xa0, v146
	s_waitcnt lgkmcnt(0)
	v_ashrrev_i32_e32 v33, 31, v32
	v_lshlrev_b64 v[34:35], 11, v[32:33]
	v_lshl_add_u64 v[34:35], v[34:35], 0, v[144:145]
	v_lshlrev_b64 v[38:39], 1, v[34:35]
	v_lshl_add_u64 v[34:35], s[14:15], 0, v[38:39]
	s_waitcnt vmcnt(21)
	s_nop 1
	v_mov_b32_e32 v34, v224
	v_mov_b32_e32 v35, v225
	v_mov_b32_e32 v36, v226
	v_mov_b32_e32 v37, v227
	v_lshl_add_u64 v[40:41], s[16:17], 0, v[38:39]
	v_or_b32_e32 v38, 0x100, v38
	v_lshl_add_u64 v[42:43], s[14:15], 0, v[38:39]
	v_lshlrev_b32_e32 v44, 16, v34
	v_and_b32_e32 v45, 0xffff0000, v34
	v_lshlrev_b32_e32 v34, 16, v35
	v_and_b32_e32 v35, 0xffff0000, v35
	v_lshlrev_b32_e32 v46, 16, v36
	v_and_b32_e32 v47, 0xffff0000, v36
	v_lshlrev_b32_e32 v36, 16, v37
	v_and_b32_e32 v37, 0xffff0000, v37
	v_pk_add_f32 v[34:35], v[30:31], v[34:35]
	v_pk_add_f32 v[44:45], v[28:29], v[44:45]
	v_pk_add_f32 v[36:37], v[26:27], v[36:37]
	v_pk_add_f32 v[46:47], v[24:25], v[46:47]
	v_cvt_pk_bf16_f32 v24, v44, v45
	v_cvt_pk_bf16_f32 v25, v34, v35
	v_mul_f32_e32 v35, v35, v35
	v_cvt_pk_bf16_f32 v26, v46, v47
	v_cvt_pk_bf16_f32 v27, v36, v37
	s_waitcnt vmcnt(20)
	s_nop 1
	v_mov_b32_e32 v28, v228
	v_mov_b32_e32 v29, v229
	v_mov_b32_e32 v30, v230
	v_mov_b32_e32 v31, v231
	v_mul_f32_e32 v42, v45, v45
	v_mul_f32_e32 v43, v47, v47
	v_fmac_f32_e32 v42, v44, v44
	v_fmac_f32_e32 v35, v34, v34
	v_mul_f32_e32 v37, v37, v37
	v_fmac_f32_e32 v43, v46, v46
	v_add_f32_e32 v34, v42, v35
	v_fmac_f32_e32 v37, v36, v36
	v_add_f32_e32 v34, v43, v34
	v_add_f32_e32 v42, v37, v34
	global_store_dwordx4 v[40:41], v[24:27], off
	v_lshlrev_b32_e32 v34, 16, v28
	v_and_b32_e32 v35, 0xffff0000, v28
	v_lshlrev_b32_e32 v28, 16, v29
	v_and_b32_e32 v29, 0xffff0000, v29
	v_lshlrev_b32_e32 v36, 16, v30
	v_and_b32_e32 v37, 0xffff0000, v30
	v_lshlrev_b32_e32 v30, 16, v31
	v_and_b32_e32 v31, 0xffff0000, v31
	v_pk_add_f32 v[22:23], v[22:23], v[28:29]
	v_pk_add_f32 v[20:21], v[20:21], v[34:35]
	v_pk_add_f32 v[28:29], v[18:19], v[30:31]
	v_pk_add_f32 v[30:31], v[16:17], v[36:37]
	v_mul_f32_e32 v16, v21, v21
	v_mul_f32_e32 v17, v23, v23
	v_mul_f32_e32 v18, v31, v31
	v_fmac_f32_e32 v16, v20, v20
	v_fmac_f32_e32 v17, v22, v22
	v_mul_f32_e32 v19, v29, v29
	v_fmac_f32_e32 v18, v30, v30
	v_add_f32_e32 v16, v16, v17
	v_add_f32_e32 v16, v18, v16
	v_fmac_f32_e32 v19, v28, v28
	v_add_f32_e32 v16, v19, v16
	v_add_f32_e32 v16, v42, v16
	ds_bpermute_b32 v17, v120, v16
	v_cvt_pk_bf16_f32 v18, v20, v21
	v_cvt_pk_bf16_f32 v19, v22, v23
	v_lshl_add_u64 v[22:23], s[16:17], 0, v[38:39]
	v_cvt_pk_bf16_f32 v20, v30, v31
	s_waitcnt lgkmcnt(0)
	v_add_f32_e32 v16, v16, v17
	ds_bpermute_b32 v17, v114, v16
	v_cvt_pk_bf16_f32 v21, v28, v29
	global_store_dwordx4 v[22:23], v[18:21], off
	s_and_saveexec_b64 s[42:43], s[2:3]
	s_cbranch_execz .LBB0_701
	v_lshl_add_u64 v[18:19], v[32:33], 2, s[18:19]
	s_waitcnt lgkmcnt(0)
	v_add_f32_e32 v16, v16, v17
	global_atomic_add_f32 v[18:19], v16, off
.LBB0_701:
	s_or_b64 exec, exec, s[42:43]
	v_add_u32_e32 v16, 0xb0, v146
	s_waitcnt lgkmcnt(0)
	v_ashrrev_i32_e32 v17, 31, v16
	v_lshlrev_b64 v[18:19], 11, v[16:17]
	v_lshl_add_u64 v[18:19], v[18:19], 0, v[144:145]
	v_lshlrev_b64 v[22:23], 1, v[18:19]
	v_lshl_add_u64 v[18:19], s[14:15], 0, v[22:23]
	s_waitcnt vmcnt(22)
	s_nop 1
	v_mov_b32_e32 v18, v232
	v_mov_b32_e32 v19, v233
	v_mov_b32_e32 v20, v234
	v_mov_b32_e32 v21, v235
	v_lshl_add_u64 v[24:25], s[16:17], 0, v[22:23]
	v_or_b32_e32 v22, 0x100, v22
	v_lshl_add_u64 v[26:27], s[14:15], 0, v[22:23]
	v_lshlrev_b32_e32 v28, 16, v18
	v_and_b32_e32 v29, 0xffff0000, v18
	v_lshlrev_b32_e32 v18, 16, v19
	v_and_b32_e32 v19, 0xffff0000, v19
	v_lshlrev_b32_e32 v30, 16, v20
	v_and_b32_e32 v31, 0xffff0000, v20
	v_lshlrev_b32_e32 v20, 16, v21
	v_and_b32_e32 v21, 0xffff0000, v21
	v_pk_add_f32 v[18:19], v[14:15], v[18:19]
	v_pk_add_f32 v[28:29], v[12:13], v[28:29]
	v_pk_add_f32 v[20:21], v[10:11], v[20:21]
	v_pk_add_f32 v[30:31], v[8:9], v[30:31]
	v_cvt_pk_bf16_f32 v8, v28, v29
	v_cvt_pk_bf16_f32 v9, v18, v19
	v_mul_f32_e32 v19, v19, v19
	v_cvt_pk_bf16_f32 v10, v30, v31
	v_cvt_pk_bf16_f32 v11, v20, v21
	s_waitcnt vmcnt(21)
	s_nop 1
	v_mov_b32_e32 v12, v236
	v_mov_b32_e32 v13, v237
	v_mov_b32_e32 v14, v238
	v_mov_b32_e32 v15, v239
	v_mul_f32_e32 v26, v29, v29
	v_mul_f32_e32 v27, v31, v31
	v_fmac_f32_e32 v26, v28, v28
	v_fmac_f32_e32 v19, v18, v18
	v_mul_f32_e32 v21, v21, v21
	v_fmac_f32_e32 v27, v30, v30
	v_add_f32_e32 v18, v26, v19
	v_fmac_f32_e32 v21, v20, v20
	v_add_f32_e32 v18, v27, v18
	v_add_f32_e32 v26, v21, v18
	global_store_dwordx4 v[24:25], v[8:11], off
	v_lshlrev_b32_e32 v18, 16, v12
	v_and_b32_e32 v19, 0xffff0000, v12
	v_lshlrev_b32_e32 v12, 16, v13
	v_and_b32_e32 v13, 0xffff0000, v13
	v_lshlrev_b32_e32 v20, 16, v14
	v_and_b32_e32 v21, 0xffff0000, v14
	v_lshlrev_b32_e32 v14, 16, v15
	v_and_b32_e32 v15, 0xffff0000, v15
	v_pk_add_f32 v[6:7], v[6:7], v[12:13]
	v_pk_add_f32 v[4:5], v[4:5], v[18:19]
	v_pk_add_f32 v[12:13], v[2:3], v[14:15]
	v_pk_add_f32 v[14:15], v[0:1], v[20:21]
	v_mul_f32_e32 v0, v5, v5
	v_mul_f32_e32 v1, v7, v7
	v_mul_f32_e32 v2, v15, v15
	v_fmac_f32_e32 v0, v4, v4
	v_fmac_f32_e32 v1, v6, v6
	v_mul_f32_e32 v3, v13, v13
	v_fmac_f32_e32 v2, v14, v14
	v_add_f32_e32 v0, v0, v1
	v_add_f32_e32 v0, v2, v0
	v_fmac_f32_e32 v3, v12, v12
	v_add_f32_e32 v0, v3, v0
	v_add_f32_e32 v0, v26, v0
	ds_bpermute_b32 v1, v120, v0
	v_cvt_pk_bf16_f32 v2, v4, v5
	v_cvt_pk_bf16_f32 v3, v6, v7
	v_lshl_add_u64 v[6:7], s[16:17], 0, v[22:23]
	v_cvt_pk_bf16_f32 v4, v14, v15
	s_waitcnt lgkmcnt(0)
	v_add_f32_e32 v0, v0, v1
	ds_bpermute_b32 v1, v114, v0
	v_cvt_pk_bf16_f32 v5, v12, v13
	global_store_dwordx4 v[6:7], v[2:5], off
	s_and_saveexec_b64 s[42:43], s[2:3]
	s_cbranch_execz .LBB0_703
	v_lshl_add_u64 v[2:3], v[16:17], 2, s[18:19]
	s_waitcnt lgkmcnt(0)
	v_add_f32_e32 v0, v0, v1
	global_atomic_add_f32 v[2:3], v0, off
